# v41 plus: 76 of the 80 LDS-DMA staging loads in the GEMM K-loops use the SADDR form (SGPR base + 32-bit VGPR offset); their 64-bit VALU address adds are gone, kstep-advanced bases are formed on the SA
# speedup vs baseline: 1.0063x; 1.0015x over previous
; #define PG8_STAGE(bufoff, gbase, voff) do { _Pragma("unroll") for (int _i = 0; _i < 2; ++_i) \
;         __builtin_amdgcn_global_load_lds((const unsigned*)((const char*)(gbase) + (voff)[_i]), (PG8_LAS unsigned*)(lds + (bufoff) + ldsw + _i * 8192), 16, 0, 0); } while (0)
; #define PG8_LDA(dst, b, h) do { _Pragma("unroll") for (int m = 0; m < 4; ++m) _Pragma("unroll") for (int k = 0; k < 2; ++k) dst[m][k] = *(const PG8_LAS bf16x8*)(lds + PG8_SA(b, h) + aoff + m * 2048 + k * 1024); } while (0)
; #define PG8_LDB(dst, b, h) do { _Pragma("unroll") for (int n = 0; n < 2; ++n) _Pragma("unroll") for (int k = 0; k < 2; ++k) dst[n][k] = *(const PG8_LAS bf16x8*)(lds + PG8_SB(b, h) + boff + n * 2048 + k * 1024); } while (0)
; #define PG8_MMA(ai, bj, At, Bt) do { __builtin_amdgcn_s_setprio(1); _Pragma("unroll") for (int m = 0; m < 4; ++m) _Pragma("unroll") for (int n = 0; n < 2; ++n) _Pragma("unroll") for (int k = 0; k < 2; ++k) \
;         acc[ai][bj][m][n] = __builtin_amdgcn_mfma_f32_16x16x32_bf16(Bt[n][k], At[m][k], acc[ai][bj][m][n], 0, 0, 0); __builtin_amdgcn_s_setprio(0); } while (0)
; #define PG8_WAIT_V(n) asm volatile("s_waitcnt vmcnt(" #n ")" ::: "memory")
; #define PG8_WAIT_L(n) asm volatile("s_waitcnt lgkmcnt(" #n ")" ::: "memory")
; #define PG8_BAR __builtin_amdgcn_s_barrier()
; template <class Epi, class Sched, bool ALIGN_EPI = false, bool SP2 = false>
; __device__ __forceinline__ void gemm_phase(PG8_LAS unsigned char* lds, const Gemm g, const Sched& S, const Epi& E) {
;     ...
;             const char* a1 = cA + (size_t)(t + 1) * kstep;
;             const char* a2 = last ? nA : cA + (size_t)(t + 2) * kstep; const char* b2 = last ? nB : cB + (size_t)(t + 2) * kstep;
;             const char* a3 = a2 + kstep; const char* b3 = b2 + kstep;
;             if (last && has_next) S.a_ready(nxt);
;             if constexpr (SP2) {
;             PG8_LDB(B0, 0, 0); PG8_LDB(B1, 0, 1); PG8_SCHED; PG8_LDA(At, 0, 0); PG8_STAGE(PG8_SA(1, 1), a1 + hstep, voffA);
;             PG8_WAIT_V(8); PG8_WAIT_L(0); PG8_BAR; PG8_MMA(0, 0, At, B0); PG8_MMA(0, 1, At, B1); PG8_BAR; PG8_SCHED;
;             PG8_LDA(At, 0, 1); PG8_STAGE(PG8_SB(0, 0), b2, voffB); PG8_STAGE(PG8_SB(0, 1), b2 + hstepB, voffB); PG8_STAGE(PG8_SA(0, 0), a2, voffA);
;             PG8_WAIT_V(8); PG8_WAIT_L(0); PG8_BAR; PG8_MMA(1, 0, At, B0); PG8_MMA(1, 1, At, B1); PG8_BAR; PG8_SCHED;
.LBB0_170:
	s_add_u32 s9, s70, s46
	s_addc_u32 s10, s71, s47
	s_add_u32 s9, s9, 0x100
	s_addc_u32 s10, s10, 0
	s_add_u32 s11, s93, s46
	s_addc_u32 s12, s94, s47
	s_add_i32 s13, 0, 0x10000
	s_cmpk_eq_i32 s46, 0xf00
	s_cselect_b32 s85, s4, s10
	s_cselect_b32 s84, s5, s9
	s_cselect_b32 s81, s6, s12
	s_cselect_b32 s80, s7, s11
	s_add_i32 s9, 0, 0x14000
	v_add_u32_e32 v160, s13, v139
	v_add_u32_e32 v178, s9, v139
	ds_read_b128 v[148:151], v160
	ds_read_b128 v[152:155], v160 offset:1024
	ds_read_b128 v[156:159], v160 offset:2048
	ds_read_b128 v[160:163], v160 offset:3072
	ds_read_b128 v[166:169], v178
	ds_read_b128 v[170:173], v178 offset:1024
	ds_read_b128 v[174:177], v178 offset:2048
	ds_read_b128 v[178:181], v178 offset:3072
	v_lshl_add_u64 v[194:195], v[144:145], 0, s[46:47]
	s_add_i32 m0, s1, 0xc000
	ds_read_b128 v[182:185], v165
	ds_read_b128 v[206:209], v165 offset:1024
	ds_read_b128 v[210:213], v165 offset:2048
	ds_read_b128 v[214:217], v165 offset:3072
	ds_read_b128 v[218:221], v165 offset:4096
	ds_read_b128 v[236:239], v165 offset:5120
	ds_read_b128 v[240:243], v165 offset:6144
	ds_read_b128 v[244:247], v165 offset:7168
	global_load_lds_dwordx4 v[194:195], off
	s_add_i32 m0, s1, 0xe000
	v_lshl_add_u64 v[194:195], v[146:147], 0, s[46:47]
	global_load_lds_dwordx4 v[194:195], off
	s_waitcnt vmcnt(8)
	s_waitcnt lgkmcnt(0)
	s_barrier
	v_mfma_f32_16x16x32_bf16 v[126:129], v[148:151], v[182:185], v[126:129]
	v_mfma_f32_16x16x32_bf16 v[122:125], v[156:159], v[182:185], v[122:125]
	v_mfma_f32_16x16x32_bf16 v[118:121], v[148:151], v[210:213], v[118:121]
	v_mfma_f32_16x16x32_bf16 v[114:117], v[156:159], v[210:213], v[114:117]
	v_mfma_f32_16x16x32_bf16 v[110:113], v[148:151], v[218:221], v[110:113]
	v_mfma_f32_16x16x32_bf16 v[106:109], v[156:159], v[218:221], v[106:109]
	v_mfma_f32_16x16x32_bf16 v[102:105], v[148:151], v[240:243], v[102:105]
	v_mfma_f32_16x16x32_bf16 v[98:101], v[156:159], v[240:243], v[98:101]
	v_mfma_f32_16x16x32_bf16 v[126:129], v[152:155], v[206:209], v[126:129]
	v_mfma_f32_16x16x32_bf16 v[122:125], v[160:163], v[206:209], v[122:125]
	v_mfma_f32_16x16x32_bf16 v[118:121], v[152:155], v[214:217], v[118:121]
	v_mfma_f32_16x16x32_bf16 v[114:117], v[160:163], v[214:217], v[114:117]
	v_mfma_f32_16x16x32_bf16 v[110:113], v[152:155], v[236:239], v[110:113]
	v_mfma_f32_16x16x32_bf16 v[106:109], v[160:163], v[236:239], v[106:109]
	v_mfma_f32_16x16x32_bf16 v[102:105], v[152:155], v[244:247], v[102:105]
	v_mfma_f32_16x16x32_bf16 v[98:101], v[160:163], v[244:247], v[98:101]
	v_mfma_f32_16x16x32_bf16 v[94:97], v[166:169], v[182:185], v[94:97]
	v_mfma_f32_16x16x32_bf16 v[90:93], v[174:177], v[182:185], v[90:93]
	v_mfma_f32_16x16x32_bf16 v[86:89], v[166:169], v[210:213], v[86:89]
	v_mfma_f32_16x16x32_bf16 v[82:85], v[174:177], v[210:213], v[82:85]
	v_mfma_f32_16x16x32_bf16 v[78:81], v[166:169], v[218:221], v[78:81]
	v_mfma_f32_16x16x32_bf16 v[74:77], v[174:177], v[218:221], v[74:77]
	v_mfma_f32_16x16x32_bf16 v[70:73], v[166:169], v[240:243], v[70:73]
	v_mfma_f32_16x16x32_bf16 v[66:69], v[174:177], v[240:243], v[66:69]
	v_mfma_f32_16x16x32_bf16 v[94:97], v[170:173], v[206:209], v[94:97]
	v_mfma_f32_16x16x32_bf16 v[90:93], v[178:181], v[206:209], v[90:93]
	v_mfma_f32_16x16x32_bf16 v[86:89], v[170:173], v[214:217], v[86:89]
	v_mfma_f32_16x16x32_bf16 v[82:85], v[178:181], v[214:217], v[82:85]
	v_mfma_f32_16x16x32_bf16 v[78:81], v[170:173], v[236:239], v[78:81]
	v_mfma_f32_16x16x32_bf16 v[74:77], v[178:181], v[236:239], v[74:77]
	v_mfma_f32_16x16x32_bf16 v[70:73], v[170:173], v[244:247], v[70:73]
	v_mfma_f32_16x16x32_bf16 v[66:69], v[178:181], v[244:247], v[66:69]
	s_barrier
	s_add_i32 s10, s13, s0
	s_mov_b32 m0, s10
	ds_read_b128 v[182:185], v165 offset:16384
	ds_read_b128 v[206:209], v165 offset:17408
	ds_read_b128 v[210:213], v165 offset:18432
	ds_read_b128 v[214:217], v165 offset:19456
	ds_read_b128 v[218:221], v165 offset:20480
	ds_read_b128 v[236:239], v165 offset:21504
	ds_read_b128 v[240:243], v165 offset:22528
	ds_read_b128 v[244:247], v165 offset:23552
	global_load_lds_dwordx4 v132, s[80:81]
	s_add_i32 m0, s10, 0x2000
	s_add_u32 s10, s80, 0x20000
	s_addc_u32 s11, s81, 0
	s_add_i32 s9, s9, s0
	global_load_lds_dwordx4 v136, s[80:81]
	s_mov_b32 m0, s9
	s_nop 0
	global_load_lds_dwordx4 v132, s[10:11]
	s_add_i32 m0, s9, 0x2000
	s_nop 0
	global_load_lds_dwordx4 v136, s[10:11]
	s_mov_b32 m0, s1
	s_nop 0
	global_load_lds_dwordx4 v130, s[84:85]
	s_mov_b32 m0, s25
	s_nop 0
	global_load_lds_dwordx4 v134, s[84:85]
	s_waitcnt vmcnt(8)
	s_waitcnt lgkmcnt(0)
	s_barrier
; #define PG8_STAGE(bufoff, gbase, voff) do { _Pragma("unroll") for (int _i = 0; _i < 2; ++_i) \
;         __builtin_amdgcn_global_load_lds((const unsigned*)((const char*)(gbase) + (voff)[_i]), (PG8_LAS unsigned*)(lds + (bufoff) + ldsw + _i * 8192), 16, 0, 0); } while (0)
; #define PG8_LDA(dst, b, h) do { _Pragma("unroll") for (int m = 0; m < 4; ++m) _Pragma("unroll") for (int k = 0; k < 2; ++k) dst[m][k] = *(const PG8_LAS bf16x8*)(lds + PG8_SA(b, h) + aoff + m * 2048 + k * 1024); } while (0)
; #define PG8_LDB(dst, b, h) do { _Pragma("unroll") for (int n = 0; n < 2; ++n) _Pragma("unroll") for (int k = 0; k < 2; ++k) dst[n][k] = *(const PG8_LAS bf16x8*)(lds + PG8_SB(b, h) + boff + n * 2048 + k * 1024); } while (0)
; #define PG8_MMA(ai, bj, At, Bt) do { __builtin_amdgcn_s_setprio(1); _Pragma("unroll") for (int m = 0; m < 4; ++m) _Pragma("unroll") for (int n = 0; n < 2; ++n) _Pragma("unroll") for (int k = 0; k < 2; ++k) \
;         acc[ai][bj][m][n] = __builtin_amdgcn_mfma_f32_16x16x32_bf16(Bt[n][k], At[m][k], acc[ai][bj][m][n], 0, 0, 0); __builtin_amdgcn_s_setprio(0); } while (0)
; #define PG8_WAIT_V(n) asm volatile("s_waitcnt vmcnt(" #n ")" ::: "memory")
; #define PG8_WAIT_L(n) asm volatile("s_waitcnt lgkmcnt(" #n ")" ::: "memory")
; #define PG8_BAR __builtin_amdgcn_s_barrier()
; #define PG8_SCHED __builtin_amdgcn_sched_barrier(0)
; template <class Epi, class Sched, bool ALIGN_EPI = false, bool SP2 = false>
; __device__ __forceinline__ void gemm_phase(PG8_LAS unsigned char* lds, const Gemm g, const Sched& S, const Epi& E) {
;     ...
;             PG8_WAIT_V(8); PG8_WAIT_L(0); PG8_BAR; PG8_MMA(1, 0, At, B0); PG8_MMA(1, 1, At, B1); PG8_BAR; PG8_SCHED;
;             PG8_LDB(B0, 1, 0); PG8_LDB(B1, 1, 1); PG8_SCHED; PG8_LDA(At, 1, 0); PG8_STAGE(PG8_SA(0, 1), a2 + hstep, voffA);
;             PG8_WAIT_V(8); PG8_WAIT_L(0); PG8_BAR; PG8_MMA(0, 0, At, B0); PG8_MMA(0, 1, At, B1); PG8_BAR; PG8_SCHED;
	v_mfma_f32_16x16x32_bf16 v[62:65], v[148:151], v[182:185], v[62:65]
	v_mfma_f32_16x16x32_bf16 v[58:61], v[156:159], v[182:185], v[58:61]
	v_mfma_f32_16x16x32_bf16 v[54:57], v[148:151], v[210:213], v[54:57]
	v_mfma_f32_16x16x32_bf16 v[50:53], v[156:159], v[210:213], v[50:53]
	v_mfma_f32_16x16x32_bf16 v[46:49], v[148:151], v[218:221], v[46:49]
	v_mfma_f32_16x16x32_bf16 v[42:45], v[156:159], v[218:221], v[42:45]
	v_mfma_f32_16x16x32_bf16 v[38:41], v[148:151], v[240:243], v[38:41]
	v_mfma_f32_16x16x32_bf16 v[34:37], v[156:159], v[240:243], v[34:37]
	v_mfma_f32_16x16x32_bf16 v[62:65], v[152:155], v[206:209], v[62:65]
	v_mfma_f32_16x16x32_bf16 v[58:61], v[160:163], v[206:209], v[58:61]
	v_mfma_f32_16x16x32_bf16 v[54:57], v[152:155], v[214:217], v[54:57]
	v_mfma_f32_16x16x32_bf16 v[50:53], v[160:163], v[214:217], v[50:53]
	v_mfma_f32_16x16x32_bf16 v[46:49], v[152:155], v[236:239], v[46:49]
	v_mfma_f32_16x16x32_bf16 v[42:45], v[160:163], v[236:239], v[42:45]
	v_mfma_f32_16x16x32_bf16 v[38:41], v[152:155], v[244:247], v[38:41]
	v_mfma_f32_16x16x32_bf16 v[34:37], v[160:163], v[244:247], v[34:37]
	v_mfma_f32_16x16x32_bf16 v[30:33], v[166:169], v[182:185], v[30:33]
	v_mfma_f32_16x16x32_bf16 v[26:29], v[174:177], v[182:185], v[26:29]
	v_mfma_f32_16x16x32_bf16 v[22:25], v[166:169], v[210:213], v[22:25]
	v_mfma_f32_16x16x32_bf16 v[18:21], v[174:177], v[210:213], v[18:21]
	v_mfma_f32_16x16x32_bf16 v[14:17], v[166:169], v[218:221], v[14:17]
	v_mfma_f32_16x16x32_bf16 v[10:13], v[174:177], v[218:221], v[10:13]
	v_mfma_f32_16x16x32_bf16 v[6:9], v[166:169], v[240:243], v[6:9]
	v_mfma_f32_16x16x32_bf16 v[2:5], v[174:177], v[240:243], v[2:5]
	v_mfma_f32_16x16x32_bf16 v[30:33], v[170:173], v[206:209], v[30:33]
	v_mfma_f32_16x16x32_bf16 v[26:29], v[178:181], v[206:209], v[26:29]
	v_mfma_f32_16x16x32_bf16 v[22:25], v[170:173], v[214:217], v[22:25]
	v_mfma_f32_16x16x32_bf16 v[18:21], v[178:181], v[214:217], v[18:21]
	v_mfma_f32_16x16x32_bf16 v[14:17], v[170:173], v[236:239], v[14:17]
	v_mfma_f32_16x16x32_bf16 v[10:13], v[178:181], v[236:239], v[10:13]
	v_mfma_f32_16x16x32_bf16 v[6:9], v[170:173], v[244:247], v[6:9]
	v_mfma_f32_16x16x32_bf16 v[2:5], v[178:181], v[244:247], v[2:5]
	s_barrier
	s_add_i32 s9, 0, 0x18000
	s_add_i32 s12, 0, 0x1c000
	v_add_u32_e32 v160, s9, v139
	v_add_u32_e32 v178, s12, v139
	ds_read_b128 v[148:151], v160
	ds_read_b128 v[152:155], v160 offset:1024
	ds_read_b128 v[156:159], v160 offset:2048
	ds_read_b128 v[160:163], v160 offset:3072
	ds_read_b128 v[166:169], v178
	ds_read_b128 v[170:173], v178 offset:1024
	ds_read_b128 v[174:177], v178 offset:2048
	ds_read_b128 v[178:181], v178 offset:3072
	s_add_u32 s10, s84, 0x80000
	s_addc_u32 s11, s85, 0
	s_mov_b32 m0, s42
	ds_read_b128 v[182:185], v165 offset:32768
	ds_read_b128 v[206:209], v165 offset:33792
	ds_read_b128 v[210:213], v165 offset:34816
	ds_read_b128 v[214:217], v165 offset:35840
	ds_read_b128 v[218:221], v165 offset:36864
	ds_read_b128 v[236:239], v165 offset:37888
	ds_read_b128 v[240:243], v165 offset:38912
	ds_read_b128 v[244:247], v165 offset:39936
	global_load_lds_dwordx4 v130, s[10:11]
	s_mov_b32 m0, s51
	s_nop 0
	global_load_lds_dwordx4 v134, s[10:11]
	s_waitcnt vmcnt(8)
	s_waitcnt lgkmcnt(0)
	s_barrier
	v_mfma_f32_16x16x32_bf16 v[126:129], v[148:151], v[182:185], v[126:129]
	v_mfma_f32_16x16x32_bf16 v[122:125], v[156:159], v[182:185], v[122:125]
	v_mfma_f32_16x16x32_bf16 v[118:121], v[148:151], v[210:213], v[118:121]
	v_mfma_f32_16x16x32_bf16 v[114:117], v[156:159], v[210:213], v[114:117]
	v_mfma_f32_16x16x32_bf16 v[110:113], v[148:151], v[218:221], v[110:113]
	v_mfma_f32_16x16x32_bf16 v[106:109], v[156:159], v[218:221], v[106:109]
	v_mfma_f32_16x16x32_bf16 v[102:105], v[148:151], v[240:243], v[102:105]
	v_mfma_f32_16x16x32_bf16 v[98:101], v[156:159], v[240:243], v[98:101]
	v_mfma_f32_16x16x32_bf16 v[126:129], v[152:155], v[206:209], v[126:129]
	v_mfma_f32_16x16x32_bf16 v[122:125], v[160:163], v[206:209], v[122:125]
	v_mfma_f32_16x16x32_bf16 v[118:121], v[152:155], v[214:217], v[118:121]
	v_mfma_f32_16x16x32_bf16 v[114:117], v[160:163], v[214:217], v[114:117]
	v_mfma_f32_16x16x32_bf16 v[110:113], v[152:155], v[236:239], v[110:113]
	v_mfma_f32_16x16x32_bf16 v[106:109], v[160:163], v[236:239], v[106:109]
	v_mfma_f32_16x16x32_bf16 v[102:105], v[152:155], v[244:247], v[102:105]
	v_mfma_f32_16x16x32_bf16 v[98:101], v[160:163], v[244:247], v[98:101]
	v_mfma_f32_16x16x32_bf16 v[94:97], v[166:169], v[182:185], v[94:97]
	v_mfma_f32_16x16x32_bf16 v[90:93], v[174:177], v[182:185], v[90:93]
	v_mfma_f32_16x16x32_bf16 v[86:89], v[166:169], v[210:213], v[86:89]
	v_mfma_f32_16x16x32_bf16 v[82:85], v[174:177], v[210:213], v[82:85]
	v_mfma_f32_16x16x32_bf16 v[78:81], v[166:169], v[218:221], v[78:81]
	v_mfma_f32_16x16x32_bf16 v[74:77], v[174:177], v[218:221], v[74:77]
	v_mfma_f32_16x16x32_bf16 v[70:73], v[166:169], v[240:243], v[70:73]
	v_mfma_f32_16x16x32_bf16 v[66:69], v[174:177], v[240:243], v[66:69]
	v_mfma_f32_16x16x32_bf16 v[94:97], v[170:173], v[206:209], v[94:97]
	v_mfma_f32_16x16x32_bf16 v[90:93], v[178:181], v[206:209], v[90:93]
	v_mfma_f32_16x16x32_bf16 v[86:89], v[170:173], v[214:217], v[86:89]
	v_mfma_f32_16x16x32_bf16 v[82:85], v[178:181], v[214:217], v[82:85]
	v_mfma_f32_16x16x32_bf16 v[78:81], v[170:173], v[236:239], v[78:81]
	v_mfma_f32_16x16x32_bf16 v[74:77], v[178:181], v[236:239], v[74:77]
	v_mfma_f32_16x16x32_bf16 v[70:73], v[170:173], v[244:247], v[70:73]
	v_mfma_f32_16x16x32_bf16 v[66:69], v[178:181], v[244:247], v[66:69]
	s_barrier
; #define PG8_STAGE(bufoff, gbase, voff) do { _Pragma("unroll") for (int _i = 0; _i < 2; ++_i) \
;         __builtin_amdgcn_global_load_lds((const unsigned*)((const char*)(gbase) + (voff)[_i]), (PG8_LAS unsigned*)(lds + (bufoff) + ldsw + _i * 8192), 16, 0, 0); } while (0)
; #define PG8_LDA(dst, b, h) do { _Pragma("unroll") for (int m = 0; m < 4; ++m) _Pragma("unroll") for (int k = 0; k < 2; ++k) dst[m][k] = *(const PG8_LAS bf16x8*)(lds + PG8_SA(b, h) + aoff + m * 2048 + k * 1024); } while (0)
; #define PG8_MMA(ai, bj, At, Bt) do { __builtin_amdgcn_s_setprio(1); _Pragma("unroll") for (int m = 0; m < 4; ++m) _Pragma("unroll") for (int n = 0; n < 2; ++n) _Pragma("unroll") for (int k = 0; k < 2; ++k) \
;         acc[ai][bj][m][n] = __builtin_amdgcn_mfma_f32_16x16x32_bf16(Bt[n][k], At[m][k], acc[ai][bj][m][n], 0, 0, 0); __builtin_amdgcn_s_setprio(0); } while (0)
; #define PG8_WAIT_V(n) asm volatile("s_waitcnt vmcnt(" #n ")" ::: "memory")
; #define PG8_WAIT_L(n) asm volatile("s_waitcnt lgkmcnt(" #n ")" ::: "memory")
; #define PG8_BAR __builtin_amdgcn_s_barrier()
; #define PG8_SCHED __builtin_amdgcn_sched_barrier(0)
; template <class Epi, class Sched, bool ALIGN_EPI = false, bool SP2 = false>
; __device__ __forceinline__ void gemm_phase(PG8_LAS unsigned char* lds, const Gemm g, const Sched& S, const Epi& E) {
;     ...
;             PG8_LDA(At, 1, 1); PG8_STAGE(PG8_SB(1, 0), b3, voffB); PG8_STAGE(PG8_SB(1, 1), b3 + hstepB, voffB); PG8_STAGE(PG8_SA(1, 0), a3, voffA);
;             PG8_WAIT_V(8); PG8_WAIT_L(0); PG8_BAR; PG8_MMA(1, 0, At, B0); PG8_MMA(1, 1, At, B1); PG8_BAR; PG8_SCHED;
	s_add_i32 s9, s9, s0
	s_mov_b32 m0, s9
	ds_read_b128 v[182:185], v165 offset:49152
	ds_read_b128 v[206:209], v165 offset:50176
	ds_read_b128 v[210:213], v165 offset:51200
	ds_read_b128 v[214:217], v165 offset:52224
	ds_read_b128 v[218:221], v165 offset:53248
	ds_read_b128 v[236:239], v165 offset:54272
	ds_read_b128 v[240:243], v165 offset:55296
	ds_read_b128 v[244:247], v165 offset:56320
	s_add_u32 s100, s80, s60
	s_addc_u32 s101, s81, s61
	global_load_lds_dwordx4 v132, s[100:101]
	s_add_i32 m0, s9, 0x2000
	s_add_u32 s10, s80, 0x20080
	s_addc_u32 s11, s81, 0
	s_add_i32 s9, s12, s0
	global_load_lds_dwordx4 v136, s[100:101]
	s_mov_b32 m0, s9
	s_nop 0
	global_load_lds_dwordx4 v132, s[10:11]
	s_add_i32 m0, s9, 0x2000
	s_nop 0
	global_load_lds_dwordx4 v136, s[10:11]
	s_mov_b32 m0, s66
	s_add_u32 s100, s84, s60
	s_addc_u32 s101, s85, s61
	global_load_lds_dwordx4 v130, s[100:101]
	s_mov_b32 m0, s67
	s_nop 0
	global_load_lds_dwordx4 v134, s[100:101]
	s_waitcnt vmcnt(8)
	s_waitcnt lgkmcnt(0)
	s_barrier
	v_mfma_f32_16x16x32_bf16 v[62:65], v[148:151], v[182:185], v[62:65]
	v_mfma_f32_16x16x32_bf16 v[58:61], v[156:159], v[182:185], v[58:61]
	v_mfma_f32_16x16x32_bf16 v[54:57], v[148:151], v[210:213], v[54:57]
	v_mfma_f32_16x16x32_bf16 v[50:53], v[156:159], v[210:213], v[50:53]
	v_mfma_f32_16x16x32_bf16 v[46:49], v[148:151], v[218:221], v[46:49]
	v_mfma_f32_16x16x32_bf16 v[42:45], v[156:159], v[218:221], v[42:45]
	v_mfma_f32_16x16x32_bf16 v[38:41], v[148:151], v[240:243], v[38:41]
	v_mfma_f32_16x16x32_bf16 v[34:37], v[156:159], v[240:243], v[34:37]
	v_mfma_f32_16x16x32_bf16 v[62:65], v[152:155], v[206:209], v[62:65]
	v_mfma_f32_16x16x32_bf16 v[58:61], v[160:163], v[206:209], v[58:61]
	v_mfma_f32_16x16x32_bf16 v[54:57], v[152:155], v[214:217], v[54:57]
	v_mfma_f32_16x16x32_bf16 v[50:53], v[160:163], v[214:217], v[50:53]
	v_mfma_f32_16x16x32_bf16 v[46:49], v[152:155], v[236:239], v[46:49]
	v_mfma_f32_16x16x32_bf16 v[42:45], v[160:163], v[236:239], v[42:45]
	v_mfma_f32_16x16x32_bf16 v[38:41], v[152:155], v[244:247], v[38:41]
	v_mfma_f32_16x16x32_bf16 v[34:37], v[160:163], v[244:247], v[34:37]
	v_mfma_f32_16x16x32_bf16 v[30:33], v[166:169], v[182:185], v[30:33]
	v_mfma_f32_16x16x32_bf16 v[26:29], v[174:177], v[182:185], v[26:29]
	v_mfma_f32_16x16x32_bf16 v[22:25], v[166:169], v[210:213], v[22:25]
	v_mfma_f32_16x16x32_bf16 v[18:21], v[174:177], v[210:213], v[18:21]
	v_mfma_f32_16x16x32_bf16 v[14:17], v[166:169], v[218:221], v[14:17]
	v_mfma_f32_16x16x32_bf16 v[10:13], v[174:177], v[218:221], v[10:13]
	v_mfma_f32_16x16x32_bf16 v[6:9], v[166:169], v[240:243], v[6:9]
	v_mfma_f32_16x16x32_bf16 v[2:5], v[174:177], v[240:243], v[2:5]
	v_mfma_f32_16x16x32_bf16 v[30:33], v[170:173], v[206:209], v[30:33]
	v_mfma_f32_16x16x32_bf16 v[26:29], v[178:181], v[206:209], v[26:29]
	v_mfma_f32_16x16x32_bf16 v[22:25], v[170:173], v[214:217], v[22:25]
	v_mfma_f32_16x16x32_bf16 v[18:21], v[178:181], v[214:217], v[18:21]
	v_mfma_f32_16x16x32_bf16 v[14:17], v[170:173], v[236:239], v[14:17]
	v_mfma_f32_16x16x32_bf16 v[10:13], v[178:181], v[236:239], v[10:13]
	v_mfma_f32_16x16x32_bf16 v[6:9], v[170:173], v[244:247], v[6:9]
	v_mfma_f32_16x16x32_bf16 v[2:5], v[178:181], v[244:247], v[2:5]
	s_barrier
	s_add_i32 s8, s8, 2
	s_add_u32 s46, s46, 0x100
	s_addc_u32 s47, s47, 0
	s_cmp_gt_u32 s8, 29
	s_cbranch_scc0 .LBB0_170
	s_and_b64 vcc, exec, s[54:55]
	s_cbranch_vccz .LBB0_173
	s_barrier

; #define PG8_STAGE(bufoff, gbase, voff) do { _Pragma("unroll") for (int _i = 0; _i < 2; ++_i) \
;         __builtin_amdgcn_global_load_lds((const unsigned*)((const char*)(gbase) + (voff)[_i]), (PG8_LAS unsigned*)(lds + (bufoff) + ldsw + _i * 8192), 16, 0, 0); } while (0)
; #define PG8_LDA(dst, b, h) do { _Pragma("unroll") for (int m = 0; m < 4; ++m) _Pragma("unroll") for (int k = 0; k < 2; ++k) dst[m][k] = *(const PG8_LAS bf16x8*)(lds + PG8_SA(b, h) + aoff + m * 2048 + k * 1024); } while (0)
; #define PG8_LDB(dst, b, h) do { _Pragma("unroll") for (int n = 0; n < 2; ++n) _Pragma("unroll") for (int k = 0; k < 2; ++k) dst[n][k] = *(const PG8_LAS bf16x8*)(lds + PG8_SB(b, h) + boff + n * 2048 + k * 1024); } while (0)
; #define PG8_MMA(ai, bj, At, Bt) do { __builtin_amdgcn_s_setprio(1); _Pragma("unroll") for (int m = 0; m < 4; ++m) _Pragma("unroll") for (int n = 0; n < 2; ++n) _Pragma("unroll") for (int k = 0; k < 2; ++k) \
;         acc[ai][bj][m][n] = __builtin_amdgcn_mfma_f32_16x16x32_bf16(Bt[n][k], At[m][k], acc[ai][bj][m][n], 0, 0, 0); __builtin_amdgcn_s_setprio(0); } while (0)
; #define PG8_WAIT_V(n) asm volatile("s_waitcnt vmcnt(" #n ")" ::: "memory")
; #define PG8_WAIT_L(n) asm volatile("s_waitcnt lgkmcnt(" #n ")" ::: "memory")
; #define PG8_BAR __builtin_amdgcn_s_barrier()
; template <class Epi, class Sched, bool ALIGN_EPI = false, bool SP2 = false>
; __device__ __forceinline__ void gemm_phase(PG8_LAS unsigned char* lds, const Gemm g, const Sched& S, const Epi& E) {
;     ...
;             const char* a1 = cA + (size_t)(t + 1) * kstep;
;             const char* a2 = last ? nA : cA + (size_t)(t + 2) * kstep; const char* b2 = last ? nB : cB + (size_t)(t + 2) * kstep;
;             const char* a3 = a2 + kstep; const char* b3 = b2 + kstep;
;             if (last && has_next) S.a_ready(nxt);
;             if constexpr (SP2) {
;             PG8_LDB(B0, 0, 0); PG8_LDB(B1, 0, 1); PG8_SCHED; PG8_LDA(At, 0, 0); PG8_STAGE(PG8_SA(1, 1), a1 + hstep, voffA);
;             PG8_WAIT_V(8); PG8_WAIT_L(0); PG8_BAR; PG8_MMA(0, 0, At, B0); PG8_MMA(0, 1, At, B1); PG8_BAR; PG8_SCHED;
;             PG8_LDA(At, 0, 1); PG8_STAGE(PG8_SB(0, 0), b2, voffB); PG8_STAGE(PG8_SB(0, 1), b2 + hstepB, voffB); PG8_STAGE(PG8_SA(0, 0), a2, voffA);
;             PG8_WAIT_V(8); PG8_WAIT_L(0); PG8_BAR; PG8_MMA(1, 0, At, B0); PG8_MMA(1, 1, At, B1); PG8_BAR; PG8_SCHED;
.LBB0_788:
	s_add_u32 s9, s68, 0xfffe0080
	s_addc_u32 s10, s69, -1
	s_add_i32 s11, 0, 0x10000
	s_cmp_eq_u32 s8, 4
	s_cselect_b32 s77, s36, s10
	s_cselect_b32 s76, s37, s9
	s_cselect_b32 s73, s4, s7
	s_cselect_b32 s72, s5, s6
	s_add_i32 s9, 0, 0x14000
	v_add_u32_e32 v54, s11, v193
	v_add_u32_e32 v150, s9, v193
	ds_read_b128 v[34:37], v54
	ds_read_b128 v[38:41], v54 offset:1024
	ds_read_b128 v[50:53], v54 offset:2048
	ds_read_b128 v[54:57], v54 offset:3072
	ds_read_b128 v[114:117], v150
	ds_read_b128 v[126:129], v150 offset:1024
	ds_read_b128 v[138:141], v150 offset:2048
	ds_read_b128 v[150:153], v150 offset:3072
	s_add_i32 m0, s66, 0xc000
	ds_read_b128 v[154:157], v217
	ds_read_b128 v[158:161], v217 offset:1024
	ds_read_b128 v[170:173], v217 offset:2048
	ds_read_b128 v[206:209], v217 offset:3072
	ds_read_b128 v[210:213], v217 offset:4096
	ds_read_b128 v[218:221], v217 offset:5120
	ds_read_b128 v[236:239], v217 offset:6144
	ds_read_b128 v[240:243], v217 offset:7168
	global_load_lds_dwordx4 v180, s[68:69]
	s_add_i32 m0, s66, 0xe000
	s_nop 0
	global_load_lds_dwordx4 v182, s[68:69]
	s_waitcnt vmcnt(8)
	s_waitcnt lgkmcnt(0)
	s_barrier
	v_mfma_f32_16x16x32_bf16 v[166:169], v[34:37], v[154:157], v[166:169]
	v_mfma_f32_16x16x32_bf16 v[162:165], v[50:53], v[154:157], v[162:165]
	v_mfma_f32_16x16x32_bf16 v[134:137], v[34:37], v[170:173], v[134:137]
	v_mfma_f32_16x16x32_bf16 v[130:133], v[50:53], v[170:173], v[130:133]
	v_mfma_f32_16x16x32_bf16 v[110:113], v[34:37], v[210:213], v[110:113]
	v_mfma_f32_16x16x32_bf16 v[106:109], v[50:53], v[210:213], v[106:109]
	v_mfma_f32_16x16x32_bf16 v[94:97], v[34:37], v[236:239], v[94:97]
	v_mfma_f32_16x16x32_bf16 v[90:93], v[50:53], v[236:239], v[90:93]
	v_mfma_f32_16x16x32_bf16 v[166:169], v[38:41], v[158:161], v[166:169]
	v_mfma_f32_16x16x32_bf16 v[162:165], v[54:57], v[158:161], v[162:165]
	v_mfma_f32_16x16x32_bf16 v[134:137], v[38:41], v[206:209], v[134:137]
	v_mfma_f32_16x16x32_bf16 v[130:133], v[54:57], v[206:209], v[130:133]
	v_mfma_f32_16x16x32_bf16 v[110:113], v[38:41], v[218:221], v[110:113]
	v_mfma_f32_16x16x32_bf16 v[106:109], v[54:57], v[218:221], v[106:109]
	v_mfma_f32_16x16x32_bf16 v[94:97], v[38:41], v[240:243], v[94:97]
	v_mfma_f32_16x16x32_bf16 v[90:93], v[54:57], v[240:243], v[90:93]
	v_mfma_f32_16x16x32_bf16 v[146:149], v[114:117], v[154:157], v[146:149]
	v_mfma_f32_16x16x32_bf16 v[142:145], v[138:141], v[154:157], v[142:145]
	v_mfma_f32_16x16x32_bf16 v[122:125], v[114:117], v[170:173], v[122:125]
	v_mfma_f32_16x16x32_bf16 v[118:121], v[138:141], v[170:173], v[118:121]
	v_mfma_f32_16x16x32_bf16 v[102:105], v[114:117], v[210:213], v[102:105]
	v_mfma_f32_16x16x32_bf16 v[98:101], v[138:141], v[210:213], v[98:101]
	v_mfma_f32_16x16x32_bf16 v[86:89], v[114:117], v[236:239], v[86:89]
	v_mfma_f32_16x16x32_bf16 v[82:85], v[138:141], v[236:239], v[82:85]
	v_mfma_f32_16x16x32_bf16 v[146:149], v[126:129], v[158:161], v[146:149]
	v_mfma_f32_16x16x32_bf16 v[142:145], v[150:153], v[158:161], v[142:145]
	v_mfma_f32_16x16x32_bf16 v[122:125], v[126:129], v[206:209], v[122:125]
	v_mfma_f32_16x16x32_bf16 v[118:121], v[150:153], v[206:209], v[118:121]
	v_mfma_f32_16x16x32_bf16 v[102:105], v[126:129], v[218:221], v[102:105]
	v_mfma_f32_16x16x32_bf16 v[98:101], v[150:153], v[218:221], v[98:101]
	v_mfma_f32_16x16x32_bf16 v[86:89], v[126:129], v[240:243], v[86:89]
	v_mfma_f32_16x16x32_bf16 v[82:85], v[150:153], v[240:243], v[82:85]
	s_barrier
	s_add_i32 s10, s11, s25
	s_mov_b32 m0, s10
	ds_read_b128 v[154:157], v217 offset:16384
	ds_read_b128 v[158:161], v217 offset:17408
	ds_read_b128 v[170:173], v217 offset:18432
	ds_read_b128 v[206:209], v217 offset:19456
	ds_read_b128 v[210:213], v217 offset:20480
	ds_read_b128 v[218:221], v217 offset:21504
	ds_read_b128 v[236:239], v217 offset:22528
	ds_read_b128 v[240:243], v217 offset:23552
	global_load_lds_dwordx4 v190, s[72:73]
	s_add_i32 m0, s10, 0x2000
	s_add_u32 s10, s72, 0x8000
	s_addc_u32 s11, s73, 0
	s_add_i32 s9, s9, s25
	global_load_lds_dwordx4 v174, s[72:73]
	s_mov_b32 m0, s9
	s_nop 0
	global_load_lds_dwordx4 v190, s[10:11]
	s_add_i32 m0, s9, 0x2000
	s_nop 0
	global_load_lds_dwordx4 v174, s[10:11]
	s_mov_b32 m0, s66
	s_nop 0
	global_load_lds_dwordx4 v178, s[76:77]
	s_mov_b32 m0, s67
	s_nop 0
	global_load_lds_dwordx4 v176, s[76:77]
	s_waitcnt vmcnt(8)
	s_waitcnt lgkmcnt(0)
	s_barrier
	v_mfma_f32_16x16x32_bf16 v[78:81], v[34:37], v[154:157], v[78:81]
	v_mfma_f32_16x16x32_bf16 v[74:77], v[50:53], v[154:157], v[74:77]
	v_mfma_f32_16x16x32_bf16 v[62:65], v[34:37], v[170:173], v[62:65]
	v_mfma_f32_16x16x32_bf16 v[58:61], v[50:53], v[170:173], v[58:61]
	v_mfma_f32_16x16x32_bf16 v[30:33], v[34:37], v[210:213], v[30:33]
	v_mfma_f32_16x16x32_bf16 v[26:29], v[50:53], v[210:213], v[26:29]
	v_mfma_f32_16x16x32_bf16 v[14:17], v[34:37], v[236:239], v[14:17]
	v_mfma_f32_16x16x32_bf16 v[10:13], v[50:53], v[236:239], v[10:13]
	v_mfma_f32_16x16x32_bf16 v[78:81], v[38:41], v[158:161], v[78:81]
	v_mfma_f32_16x16x32_bf16 v[74:77], v[54:57], v[158:161], v[74:77]
	v_mfma_f32_16x16x32_bf16 v[62:65], v[38:41], v[206:209], v[62:65]
	v_mfma_f32_16x16x32_bf16 v[58:61], v[54:57], v[206:209], v[58:61]
	v_mfma_f32_16x16x32_bf16 v[30:33], v[38:41], v[218:221], v[30:33]
	v_mfma_f32_16x16x32_bf16 v[26:29], v[54:57], v[218:221], v[26:29]
	v_mfma_f32_16x16x32_bf16 v[14:17], v[38:41], v[240:243], v[14:17]
	v_mfma_f32_16x16x32_bf16 v[10:13], v[54:57], v[240:243], v[10:13]
	v_mfma_f32_16x16x32_bf16 v[46:49], v[114:117], v[170:173], v[46:49]
	v_mfma_f32_16x16x32_bf16 v[42:45], v[138:141], v[170:173], v[42:45]
	v_mfma_f32_16x16x32_bf16 v[22:25], v[114:117], v[210:213], v[22:25]
	v_mfma_f32_16x16x32_bf16 v[18:21], v[138:141], v[210:213], v[18:21]
	v_mfma_f32_16x16x32_bf16 v[6:9], v[114:117], v[236:239], v[6:9]
	v_mfma_f32_16x16x32_bf16 v[2:5], v[138:141], v[236:239], v[2:5]
	v_mfma_f32_16x16x32_bf16 v[34:37], v[114:117], v[154:157], v[70:73]
	v_mfma_f32_16x16x32_bf16 v[38:41], v[138:141], v[154:157], v[66:69]
	v_mfma_f32_16x16x32_bf16 v[46:49], v[126:129], v[206:209], v[46:49]
	v_mfma_f32_16x16x32_bf16 v[42:45], v[150:153], v[206:209], v[42:45]
	v_mfma_f32_16x16x32_bf16 v[22:25], v[126:129], v[218:221], v[22:25]
	v_mfma_f32_16x16x32_bf16 v[18:21], v[150:153], v[218:221], v[18:21]
	v_mfma_f32_16x16x32_bf16 v[6:9], v[126:129], v[240:243], v[6:9]
	v_mfma_f32_16x16x32_bf16 v[2:5], v[150:153], v[240:243], v[2:5]
	v_mfma_f32_16x16x32_bf16 v[34:37], v[126:129], v[158:161], v[34:37]
	v_mfma_f32_16x16x32_bf16 v[38:41], v[150:153], v[158:161], v[38:41]
	s_barrier
; #define PG8_STAGE(bufoff, gbase, voff) do { _Pragma("unroll") for (int _i = 0; _i < 2; ++_i) \
;         __builtin_amdgcn_global_load_lds((const unsigned*)((const char*)(gbase) + (voff)[_i]), (PG8_LAS unsigned*)(lds + (bufoff) + ldsw + _i * 8192), 16, 0, 0); } while (0)
; #define PG8_LDA(dst, b, h) do { _Pragma("unroll") for (int m = 0; m < 4; ++m) _Pragma("unroll") for (int k = 0; k < 2; ++k) dst[m][k] = *(const PG8_LAS bf16x8*)(lds + PG8_SA(b, h) + aoff + m * 2048 + k * 1024); } while (0)
; #define PG8_LDB(dst, b, h) do { _Pragma("unroll") for (int n = 0; n < 2; ++n) _Pragma("unroll") for (int k = 0; k < 2; ++k) dst[n][k] = *(const PG8_LAS bf16x8*)(lds + PG8_SB(b, h) + boff + n * 2048 + k * 1024); } while (0)
; #define PG8_MMA(ai, bj, At, Bt) do { __builtin_amdgcn_s_setprio(1); _Pragma("unroll") for (int m = 0; m < 4; ++m) _Pragma("unroll") for (int n = 0; n < 2; ++n) _Pragma("unroll") for (int k = 0; k < 2; ++k) \
;         acc[ai][bj][m][n] = __builtin_amdgcn_mfma_f32_16x16x32_bf16(Bt[n][k], At[m][k], acc[ai][bj][m][n], 0, 0, 0); __builtin_amdgcn_s_setprio(0); } while (0)
; #define PG8_WAIT_V(n) asm volatile("s_waitcnt vmcnt(" #n ")" ::: "memory")
; #define PG8_WAIT_L(n) asm volatile("s_waitcnt lgkmcnt(" #n ")" ::: "memory")
; #define PG8_BAR __builtin_amdgcn_s_barrier()
; #define PG8_SCHED __builtin_amdgcn_sched_barrier(0)
; template <class Epi, class Sched, bool ALIGN_EPI = false, bool SP2 = false>
; __device__ __forceinline__ void gemm_phase(PG8_LAS unsigned char* lds, const Gemm g, const Sched& S, const Epi& E) {
;     ...
;             PG8_LDB(B0, 1, 0); PG8_LDB(B1, 1, 1); PG8_SCHED; PG8_LDA(At, 1, 0); PG8_STAGE(PG8_SA(0, 1), a2 + hstep, voffA);
;             PG8_WAIT_V(8); PG8_WAIT_L(0); PG8_BAR; PG8_MMA(0, 0, At, B0); PG8_MMA(0, 1, At, B1); PG8_BAR; PG8_SCHED;
;             PG8_LDA(At, 1, 1); PG8_STAGE(PG8_SB(1, 0), b3, voffB); PG8_STAGE(PG8_SB(1, 1), b3 + hstepB, voffB); PG8_STAGE(PG8_SA(1, 0), a3, voffA);
;             PG8_WAIT_V(8); PG8_WAIT_L(0); PG8_BAR; PG8_MMA(1, 0, At, B0); PG8_MMA(1, 1, At, B1); PG8_BAR; PG8_SCHED;
	s_add_i32 s9, 0, 0x18000
	s_add_i32 s12, 0, 0x1c000
	v_add_u32_e32 v70, s9, v193
	v_add_u32_e32 v150, s12, v193
	ds_read_b128 v[50:53], v70
	ds_read_b128 v[54:57], v70 offset:1024
	ds_read_b128 v[66:69], v70 offset:2048
	ds_read_b128 v[70:73], v70 offset:3072
	ds_read_b128 v[114:117], v150
	ds_read_b128 v[126:129], v150 offset:1024
	ds_read_b128 v[138:141], v150 offset:2048
	ds_read_b128 v[150:153], v150 offset:3072
	s_add_u32 s10, s76, 0x20000
	s_addc_u32 s11, s77, 0
	s_mov_b32 m0, s80
	ds_read_b128 v[154:157], v217 offset:32768
	ds_read_b128 v[158:161], v217 offset:33792
	ds_read_b128 v[170:173], v217 offset:34816
	ds_read_b128 v[206:209], v217 offset:35840
	ds_read_b128 v[210:213], v217 offset:36864
	ds_read_b128 v[218:221], v217 offset:37888
	ds_read_b128 v[236:239], v217 offset:38912
	ds_read_b128 v[240:243], v217 offset:39936
	global_load_lds_dwordx4 v178, s[10:11]
	s_mov_b32 m0, s81
	s_nop 0
	global_load_lds_dwordx4 v176, s[10:11]
	s_waitcnt vmcnt(8)
	s_waitcnt lgkmcnt(0)
	s_barrier
	v_mfma_f32_16x16x32_bf16 v[166:169], v[50:53], v[154:157], v[166:169]
	v_mfma_f32_16x16x32_bf16 v[162:165], v[66:69], v[154:157], v[162:165]
	v_mfma_f32_16x16x32_bf16 v[134:137], v[50:53], v[170:173], v[134:137]
	v_mfma_f32_16x16x32_bf16 v[130:133], v[66:69], v[170:173], v[130:133]
	v_mfma_f32_16x16x32_bf16 v[110:113], v[50:53], v[210:213], v[110:113]
	v_mfma_f32_16x16x32_bf16 v[106:109], v[66:69], v[210:213], v[106:109]
	v_mfma_f32_16x16x32_bf16 v[94:97], v[50:53], v[236:239], v[94:97]
	v_mfma_f32_16x16x32_bf16 v[90:93], v[66:69], v[236:239], v[90:93]
	v_mfma_f32_16x16x32_bf16 v[166:169], v[54:57], v[158:161], v[166:169]
	v_mfma_f32_16x16x32_bf16 v[162:165], v[70:73], v[158:161], v[162:165]
	v_mfma_f32_16x16x32_bf16 v[134:137], v[54:57], v[206:209], v[134:137]
	v_mfma_f32_16x16x32_bf16 v[130:133], v[70:73], v[206:209], v[130:133]
	v_mfma_f32_16x16x32_bf16 v[110:113], v[54:57], v[218:221], v[110:113]
	v_mfma_f32_16x16x32_bf16 v[106:109], v[70:73], v[218:221], v[106:109]
	v_mfma_f32_16x16x32_bf16 v[94:97], v[54:57], v[240:243], v[94:97]
	v_mfma_f32_16x16x32_bf16 v[90:93], v[70:73], v[240:243], v[90:93]
	v_mfma_f32_16x16x32_bf16 v[146:149], v[114:117], v[154:157], v[146:149]
	v_mfma_f32_16x16x32_bf16 v[142:145], v[138:141], v[154:157], v[142:145]
	v_mfma_f32_16x16x32_bf16 v[122:125], v[114:117], v[170:173], v[122:125]
	v_mfma_f32_16x16x32_bf16 v[118:121], v[138:141], v[170:173], v[118:121]
	v_mfma_f32_16x16x32_bf16 v[102:105], v[114:117], v[210:213], v[102:105]
	v_mfma_f32_16x16x32_bf16 v[98:101], v[138:141], v[210:213], v[98:101]
	v_mfma_f32_16x16x32_bf16 v[86:89], v[114:117], v[236:239], v[86:89]
	v_mfma_f32_16x16x32_bf16 v[82:85], v[138:141], v[236:239], v[82:85]
	v_mfma_f32_16x16x32_bf16 v[146:149], v[126:129], v[158:161], v[146:149]
	v_mfma_f32_16x16x32_bf16 v[142:145], v[150:153], v[158:161], v[142:145]
	v_mfma_f32_16x16x32_bf16 v[122:125], v[126:129], v[206:209], v[122:125]
	v_mfma_f32_16x16x32_bf16 v[118:121], v[150:153], v[206:209], v[118:121]
	v_mfma_f32_16x16x32_bf16 v[102:105], v[126:129], v[218:221], v[102:105]
	v_mfma_f32_16x16x32_bf16 v[98:101], v[150:153], v[218:221], v[98:101]
	v_mfma_f32_16x16x32_bf16 v[86:89], v[126:129], v[240:243], v[86:89]
	v_mfma_f32_16x16x32_bf16 v[82:85], v[150:153], v[240:243], v[82:85]
	s_barrier
	s_add_i32 s9, s9, s25
	s_mov_b32 m0, s9
	ds_read_b128 v[154:157], v217 offset:49152
	ds_read_b128 v[158:161], v217 offset:50176
	ds_read_b128 v[170:173], v217 offset:51200
	ds_read_b128 v[206:209], v217 offset:52224
	ds_read_b128 v[210:213], v217 offset:53248
	ds_read_b128 v[218:221], v217 offset:54272
	ds_read_b128 v[236:239], v217 offset:55296
	ds_read_b128 v[240:243], v217 offset:56320
	s_add_u32 s100, s72, s60
	s_addc_u32 s101, s73, s61
	global_load_lds_dwordx4 v190, s[100:101]
	s_add_i32 m0, s9, 0x2000
	s_add_u32 s10, s72, 0x8080
	s_addc_u32 s11, s73, 0
	s_add_i32 s9, s12, s25
	global_load_lds_dwordx4 v174, s[100:101]
	s_mov_b32 m0, s9
	s_nop 0
	global_load_lds_dwordx4 v190, s[10:11]
	s_add_i32 m0, s9, 0x2000
	s_nop 0
	global_load_lds_dwordx4 v174, s[10:11]
	s_mov_b32 m0, s82
	s_add_u32 s100, s76, s60
	s_addc_u32 s101, s77, s61
	global_load_lds_dwordx4 v178, s[100:101]
	s_mov_b32 m0, s92
	s_nop 0
	global_load_lds_dwordx4 v176, s[100:101]
	s_waitcnt vmcnt(8)
	s_waitcnt lgkmcnt(0)
	s_barrier
	v_mfma_f32_16x16x32_bf16 v[78:81], v[50:53], v[154:157], v[78:81]
	v_mfma_f32_16x16x32_bf16 v[74:77], v[66:69], v[154:157], v[74:77]
	v_mfma_f32_16x16x32_bf16 v[62:65], v[50:53], v[170:173], v[62:65]
	v_mfma_f32_16x16x32_bf16 v[58:61], v[66:69], v[170:173], v[58:61]
	v_mfma_f32_16x16x32_bf16 v[30:33], v[50:53], v[210:213], v[30:33]
	v_mfma_f32_16x16x32_bf16 v[26:29], v[66:69], v[210:213], v[26:29]
	v_mfma_f32_16x16x32_bf16 v[14:17], v[50:53], v[236:239], v[14:17]
	v_mfma_f32_16x16x32_bf16 v[10:13], v[66:69], v[236:239], v[10:13]
	v_mfma_f32_16x16x32_bf16 v[78:81], v[54:57], v[158:161], v[78:81]
	v_mfma_f32_16x16x32_bf16 v[74:77], v[70:73], v[158:161], v[74:77]
	v_mfma_f32_16x16x32_bf16 v[62:65], v[54:57], v[206:209], v[62:65]
	v_mfma_f32_16x16x32_bf16 v[58:61], v[70:73], v[206:209], v[58:61]
	v_mfma_f32_16x16x32_bf16 v[30:33], v[54:57], v[218:221], v[30:33]
	v_mfma_f32_16x16x32_bf16 v[26:29], v[70:73], v[218:221], v[26:29]
	v_mfma_f32_16x16x32_bf16 v[14:17], v[54:57], v[240:243], v[14:17]
	v_mfma_f32_16x16x32_bf16 v[10:13], v[70:73], v[240:243], v[10:13]
	v_mfma_f32_16x16x32_bf16 v[34:37], v[114:117], v[154:157], v[34:37]
	v_mfma_f32_16x16x32_bf16 v[70:73], v[126:129], v[158:161], v[34:37]
	v_mfma_f32_16x16x32_bf16 v[34:37], v[138:141], v[154:157], v[38:41]
	v_mfma_f32_16x16x32_bf16 v[66:69], v[150:153], v[158:161], v[34:37]
	v_mfma_f32_16x16x32_bf16 v[34:37], v[114:117], v[170:173], v[46:49]
	v_mfma_f32_16x16x32_bf16 v[46:49], v[126:129], v[206:209], v[34:37]
	v_mfma_f32_16x16x32_bf16 v[34:37], v[138:141], v[170:173], v[42:45]
	v_mfma_f32_16x16x32_bf16 v[22:25], v[114:117], v[210:213], v[22:25]
	v_mfma_f32_16x16x32_bf16 v[18:21], v[138:141], v[210:213], v[18:21]
	v_mfma_f32_16x16x32_bf16 v[6:9], v[114:117], v[236:239], v[6:9]
	v_mfma_f32_16x16x32_bf16 v[2:5], v[138:141], v[236:239], v[2:5]
	v_mfma_f32_16x16x32_bf16 v[42:45], v[150:153], v[206:209], v[34:37]
	v_mfma_f32_16x16x32_bf16 v[22:25], v[126:129], v[218:221], v[22:25]
	v_mfma_f32_16x16x32_bf16 v[18:21], v[150:153], v[218:221], v[18:21]
	v_mfma_f32_16x16x32_bf16 v[6:9], v[126:129], v[240:243], v[6:9]
	v_mfma_f32_16x16x32_bf16 v[2:5], v[150:153], v[240:243], v[2:5]
	s_barrier
	s_add_i32 s8, s8, 2
	s_add_u32 s68, s68, 0x100
	s_addc_u32 s69, s69, 0
	s_add_u32 s6, s6, 0x100
	s_addc_u32 s7, s7, 0
	s_cmp_gt_u32 s8, 5
	s_cbranch_scc0 .LBB0_788
	s_and_b64 vcc, exec, s[46:47]
	s_cbranch_vccz .LBB0_791
	s_barrier

; #define PG8_STAGE(bufoff, gbase, voff) do { _Pragma("unroll") for (int _i = 0; _i < 2; ++_i) \
;         __builtin_amdgcn_global_load_lds((const unsigned*)((const char*)(gbase) + (voff)[_i]), (PG8_LAS unsigned*)(lds + (bufoff) + ldsw + _i * 8192), 16, 0, 0); } while (0)
; #define PG8_LDA(dst, b, h) do { _Pragma("unroll") for (int m = 0; m < 4; ++m) _Pragma("unroll") for (int k = 0; k < 2; ++k) dst[m][k] = *(const PG8_LAS bf16x8*)(lds + PG8_SA(b, h) + aoff + m * 2048 + k * 1024); } while (0)
; #define PG8_LDB(dst, b, h) do { _Pragma("unroll") for (int n = 0; n < 2; ++n) _Pragma("unroll") for (int k = 0; k < 2; ++k) dst[n][k] = *(const PG8_LAS bf16x8*)(lds + PG8_SB(b, h) + boff + n * 2048 + k * 1024); } while (0)
; #define PG8_MMA(ai, bj, At, Bt) do { __builtin_amdgcn_s_setprio(1); _Pragma("unroll") for (int m = 0; m < 4; ++m) _Pragma("unroll") for (int n = 0; n < 2; ++n) _Pragma("unroll") for (int k = 0; k < 2; ++k) \
;         acc[ai][bj][m][n] = __builtin_amdgcn_mfma_f32_16x16x32_bf16(Bt[n][k], At[m][k], acc[ai][bj][m][n], 0, 0, 0); __builtin_amdgcn_s_setprio(0); } while (0)
; #define PG8_WAIT_V(n) asm volatile("s_waitcnt vmcnt(" #n ")" ::: "memory")
; #define PG8_WAIT_L(n) asm volatile("s_waitcnt lgkmcnt(" #n ")" ::: "memory")
; #define PG8_BAR __builtin_amdgcn_s_barrier()
; template <class Epi, class Sched, bool ALIGN_EPI = false, bool SP2 = false>
; __device__ __forceinline__ void gemm_phase(PG8_LAS unsigned char* lds, const Gemm g, const Sched& S, const Epi& E) {
;     ...
;             const char* a1 = cA + (size_t)(t + 1) * kstep;
;             const char* a2 = last ? nA : cA + (size_t)(t + 2) * kstep; const char* b2 = last ? nB : cB + (size_t)(t + 2) * kstep;
;             const char* a3 = a2 + kstep; const char* b3 = b2 + kstep;
;             if (last && has_next) S.a_ready(nxt);
;             if constexpr (SP2) {
;             PG8_LDB(B0, 0, 0); PG8_LDB(B1, 0, 1); PG8_SCHED; PG8_LDA(At, 0, 0); PG8_STAGE(PG8_SA(1, 1), a1 + hstep, voffA);
;             PG8_WAIT_V(8); PG8_WAIT_L(0); PG8_BAR; PG8_MMA(0, 0, At, B0); PG8_MMA(0, 1, At, B1); PG8_BAR; PG8_SCHED;
;             PG8_LDA(At, 0, 1); PG8_STAGE(PG8_SB(0, 0), b2, voffB); PG8_STAGE(PG8_SB(0, 1), b2 + hstepB, voffB); PG8_STAGE(PG8_SA(0, 0), a2, voffA);
;             PG8_WAIT_V(8); PG8_WAIT_L(0); PG8_BAR; PG8_MMA(1, 0, At, B0); PG8_MMA(1, 1, At, B1); PG8_BAR; PG8_SCHED;
.LBB0_927:
	s_add_u32 s9, s38, 0xfff80080
	s_addc_u32 s10, s39, -1
	s_add_i32 s11, 0, 0x10000
	s_cmp_eq_u32 s8, 28
	s_cselect_b32 s95, s36, s10
	s_cselect_b32 s94, s37, s9
	s_cselect_b32 s47, s4, s7
	s_cselect_b32 s46, s5, s6
	s_add_i32 s9, 0, 0x14000
	v_add_u32_e32 v86, s11, v193
	v_add_u32_e32 v158, s9, v193
	ds_read_b128 v[66:69], v86
	ds_read_b128 v[70:73], v86 offset:1024
	ds_read_b128 v[78:81], v86 offset:2048
	ds_read_b128 v[86:89], v86 offset:3072
	ds_read_b128 v[146:149], v158
	ds_read_b128 v[150:153], v158 offset:1024
	ds_read_b128 v[154:157], v158 offset:2048
	ds_read_b128 v[158:161], v158 offset:3072
	s_add_i32 m0, s66, 0xc000
	ds_read_b128 v[162:165], v236
	ds_read_b128 v[166:169], v236 offset:1024
	ds_read_b128 v[170:173], v236 offset:2048
	ds_read_b128 v[174:177], v236 offset:3072
	ds_read_b128 v[178:181], v236 offset:4096
	ds_read_b128 v[182:185], v236 offset:5120
	ds_read_b128 v[216:219], v236 offset:6144
	ds_read_b128 v[220:223], v236 offset:7168
	global_load_lds_dwordx4 v212, s[38:39]
	s_add_i32 m0, s66, 0xe000
	s_nop 0
	global_load_lds_dwordx4 v214, s[38:39]
	s_waitcnt vmcnt(8)
	s_waitcnt lgkmcnt(0)
	s_barrier
	v_mfma_f32_16x16x32_bf16 v[142:145], v[66:69], v[162:165], v[142:145]
	v_mfma_f32_16x16x32_bf16 v[138:141], v[78:81], v[162:165], v[138:141]
	v_mfma_f32_16x16x32_bf16 v[126:129], v[66:69], v[170:173], v[126:129]
	v_mfma_f32_16x16x32_bf16 v[122:125], v[78:81], v[170:173], v[122:125]
	v_mfma_f32_16x16x32_bf16 v[110:113], v[66:69], v[178:181], v[110:113]
	v_mfma_f32_16x16x32_bf16 v[106:109], v[78:81], v[178:181], v[106:109]
	v_mfma_f32_16x16x32_bf16 v[94:97], v[66:69], v[216:219], v[94:97]
	v_mfma_f32_16x16x32_bf16 v[90:93], v[78:81], v[216:219], v[90:93]
	v_mfma_f32_16x16x32_bf16 v[142:145], v[70:73], v[166:169], v[142:145]
	v_mfma_f32_16x16x32_bf16 v[138:141], v[86:89], v[166:169], v[138:141]
	v_mfma_f32_16x16x32_bf16 v[126:129], v[70:73], v[174:177], v[126:129]
	v_mfma_f32_16x16x32_bf16 v[122:125], v[86:89], v[174:177], v[122:125]
	v_mfma_f32_16x16x32_bf16 v[110:113], v[70:73], v[182:185], v[110:113]
	v_mfma_f32_16x16x32_bf16 v[106:109], v[86:89], v[182:185], v[106:109]
	v_mfma_f32_16x16x32_bf16 v[94:97], v[70:73], v[220:223], v[94:97]
	v_mfma_f32_16x16x32_bf16 v[90:93], v[86:89], v[220:223], v[90:93]
	v_mfma_f32_16x16x32_bf16 v[134:137], v[146:149], v[162:165], v[134:137]
	v_mfma_f32_16x16x32_bf16 v[130:133], v[154:157], v[162:165], v[130:133]
	v_mfma_f32_16x16x32_bf16 v[118:121], v[146:149], v[170:173], v[118:121]
	v_mfma_f32_16x16x32_bf16 v[114:117], v[154:157], v[170:173], v[114:117]
	v_mfma_f32_16x16x32_bf16 v[102:105], v[146:149], v[178:181], v[102:105]
	v_mfma_f32_16x16x32_bf16 v[98:101], v[154:157], v[178:181], v[98:101]
	v_mfma_f32_16x16x32_bf16 v[82:85], v[146:149], v[216:219], v[82:85]
	v_mfma_f32_16x16x32_bf16 v[74:77], v[154:157], v[216:219], v[74:77]
	v_mfma_f32_16x16x32_bf16 v[134:137], v[150:153], v[166:169], v[134:137]
	v_mfma_f32_16x16x32_bf16 v[130:133], v[158:161], v[166:169], v[130:133]
	v_mfma_f32_16x16x32_bf16 v[118:121], v[150:153], v[174:177], v[118:121]
	v_mfma_f32_16x16x32_bf16 v[114:117], v[158:161], v[174:177], v[114:117]
	v_mfma_f32_16x16x32_bf16 v[102:105], v[150:153], v[182:185], v[102:105]
	v_mfma_f32_16x16x32_bf16 v[98:101], v[158:161], v[182:185], v[98:101]
	v_mfma_f32_16x16x32_bf16 v[82:85], v[150:153], v[220:223], v[82:85]
	v_mfma_f32_16x16x32_bf16 v[74:77], v[158:161], v[220:223], v[74:77]
	s_barrier
	s_add_i32 s10, s11, s25
	s_mov_b32 m0, s10
	ds_read_b128 v[162:165], v236 offset:16384
	ds_read_b128 v[166:169], v236 offset:17408
	ds_read_b128 v[170:173], v236 offset:18432
	ds_read_b128 v[174:177], v236 offset:19456
	ds_read_b128 v[178:181], v236 offset:20480
	ds_read_b128 v[182:185], v236 offset:21504
	ds_read_b128 v[216:219], v236 offset:22528
	ds_read_b128 v[220:223], v236 offset:23552
	global_load_lds_dwordx4 v190, s[46:47]
	s_add_i32 m0, s10, 0x2000
	s_add_u32 s10, s46, 0x20000
	s_addc_u32 s11, s47, 0
	s_add_i32 s9, s9, s25
	global_load_lds_dwordx4 v206, s[46:47]
	s_mov_b32 m0, s9
	s_nop 0
	global_load_lds_dwordx4 v190, s[10:11]
	s_add_i32 m0, s9, 0x2000
	s_nop 0
	global_load_lds_dwordx4 v206, s[10:11]
	s_mov_b32 m0, s66
	s_nop 0
	global_load_lds_dwordx4 v210, s[94:95]
	s_mov_b32 m0, s67
	s_nop 0
	global_load_lds_dwordx4 v208, s[94:95]
	s_waitcnt vmcnt(8)
	s_waitcnt lgkmcnt(0)
	s_barrier
	v_mfma_f32_16x16x32_bf16 v[62:65], v[66:69], v[162:165], v[62:65]
	v_mfma_f32_16x16x32_bf16 v[58:61], v[78:81], v[162:165], v[58:61]
	v_mfma_f32_16x16x32_bf16 v[46:49], v[66:69], v[170:173], v[46:49]
	v_mfma_f32_16x16x32_bf16 v[42:45], v[78:81], v[170:173], v[42:45]
	v_mfma_f32_16x16x32_bf16 v[30:33], v[66:69], v[178:181], v[30:33]
	v_mfma_f32_16x16x32_bf16 v[26:29], v[78:81], v[178:181], v[26:29]
	v_mfma_f32_16x16x32_bf16 v[14:17], v[66:69], v[216:219], v[14:17]
	v_mfma_f32_16x16x32_bf16 v[10:13], v[78:81], v[216:219], v[10:13]
	v_mfma_f32_16x16x32_bf16 v[62:65], v[70:73], v[166:169], v[62:65]
	v_mfma_f32_16x16x32_bf16 v[58:61], v[86:89], v[166:169], v[58:61]
	v_mfma_f32_16x16x32_bf16 v[46:49], v[70:73], v[174:177], v[46:49]
	v_mfma_f32_16x16x32_bf16 v[42:45], v[86:89], v[174:177], v[42:45]
	v_mfma_f32_16x16x32_bf16 v[30:33], v[70:73], v[182:185], v[30:33]
	v_mfma_f32_16x16x32_bf16 v[26:29], v[86:89], v[182:185], v[26:29]
	v_mfma_f32_16x16x32_bf16 v[14:17], v[70:73], v[220:223], v[14:17]
	v_mfma_f32_16x16x32_bf16 v[10:13], v[86:89], v[220:223], v[10:13]
	v_mfma_f32_16x16x32_bf16 v[54:57], v[146:149], v[162:165], v[54:57]
	v_mfma_f32_16x16x32_bf16 v[50:53], v[154:157], v[162:165], v[50:53]
	v_mfma_f32_16x16x32_bf16 v[38:41], v[146:149], v[170:173], v[38:41]
	v_mfma_f32_16x16x32_bf16 v[34:37], v[154:157], v[170:173], v[34:37]
	v_mfma_f32_16x16x32_bf16 v[22:25], v[146:149], v[178:181], v[22:25]
	v_mfma_f32_16x16x32_bf16 v[18:21], v[154:157], v[178:181], v[18:21]
	v_mfma_f32_16x16x32_bf16 v[6:9], v[146:149], v[216:219], v[6:9]
	v_mfma_f32_16x16x32_bf16 v[2:5], v[154:157], v[216:219], v[2:5]
	v_mfma_f32_16x16x32_bf16 v[54:57], v[150:153], v[166:169], v[54:57]
	v_mfma_f32_16x16x32_bf16 v[50:53], v[158:161], v[166:169], v[50:53]
	v_mfma_f32_16x16x32_bf16 v[38:41], v[150:153], v[174:177], v[38:41]
	v_mfma_f32_16x16x32_bf16 v[34:37], v[158:161], v[174:177], v[34:37]
	v_mfma_f32_16x16x32_bf16 v[22:25], v[150:153], v[182:185], v[22:25]
	v_mfma_f32_16x16x32_bf16 v[18:21], v[158:161], v[182:185], v[18:21]
	v_mfma_f32_16x16x32_bf16 v[6:9], v[150:153], v[220:223], v[6:9]
	v_mfma_f32_16x16x32_bf16 v[2:5], v[158:161], v[220:223], v[2:5]
	s_barrier
; #define PG8_STAGE(bufoff, gbase, voff) do { _Pragma("unroll") for (int _i = 0; _i < 2; ++_i) \
;         __builtin_amdgcn_global_load_lds((const unsigned*)((const char*)(gbase) + (voff)[_i]), (PG8_LAS unsigned*)(lds + (bufoff) + ldsw + _i * 8192), 16, 0, 0); } while (0)
; #define PG8_LDA(dst, b, h) do { _Pragma("unroll") for (int m = 0; m < 4; ++m) _Pragma("unroll") for (int k = 0; k < 2; ++k) dst[m][k] = *(const PG8_LAS bf16x8*)(lds + PG8_SA(b, h) + aoff + m * 2048 + k * 1024); } while (0)
; #define PG8_LDB(dst, b, h) do { _Pragma("unroll") for (int n = 0; n < 2; ++n) _Pragma("unroll") for (int k = 0; k < 2; ++k) dst[n][k] = *(const PG8_LAS bf16x8*)(lds + PG8_SB(b, h) + boff + n * 2048 + k * 1024); } while (0)
; #define PG8_MMA(ai, bj, At, Bt) do { __builtin_amdgcn_s_setprio(1); _Pragma("unroll") for (int m = 0; m < 4; ++m) _Pragma("unroll") for (int n = 0; n < 2; ++n) _Pragma("unroll") for (int k = 0; k < 2; ++k) \
;         acc[ai][bj][m][n] = __builtin_amdgcn_mfma_f32_16x16x32_bf16(Bt[n][k], At[m][k], acc[ai][bj][m][n], 0, 0, 0); __builtin_amdgcn_s_setprio(0); } while (0)
; #define PG8_WAIT_V(n) asm volatile("s_waitcnt vmcnt(" #n ")" ::: "memory")
; #define PG8_WAIT_L(n) asm volatile("s_waitcnt lgkmcnt(" #n ")" ::: "memory")
; #define PG8_BAR __builtin_amdgcn_s_barrier()
; #define PG8_SCHED __builtin_amdgcn_sched_barrier(0)
; template <class Epi, class Sched, bool ALIGN_EPI = false, bool SP2 = false>
; __device__ __forceinline__ void gemm_phase(PG8_LAS unsigned char* lds, const Gemm g, const Sched& S, const Epi& E) {
;     ...
;             PG8_LDB(B0, 1, 0); PG8_LDB(B1, 1, 1); PG8_SCHED; PG8_LDA(At, 1, 0); PG8_STAGE(PG8_SA(0, 1), a2 + hstep, voffA);
;             PG8_WAIT_V(8); PG8_WAIT_L(0); PG8_BAR; PG8_MMA(0, 0, At, B0); PG8_MMA(0, 1, At, B1); PG8_BAR; PG8_SCHED;
;             PG8_LDA(At, 1, 1); PG8_STAGE(PG8_SB(1, 0), b3, voffB); PG8_STAGE(PG8_SB(1, 1), b3 + hstepB, voffB); PG8_STAGE(PG8_SA(1, 0), a3, voffA);
;             PG8_WAIT_V(8); PG8_WAIT_L(0); PG8_BAR; PG8_MMA(1, 0, At, B0); PG8_MMA(1, 1, At, B1); PG8_BAR; PG8_SCHED;
	s_add_i32 s9, 0, 0x18000
	s_add_i32 s12, 0, 0x1c000
	v_add_u32_e32 v86, s9, v193
	v_add_u32_e32 v158, s12, v193
	ds_read_b128 v[66:69], v86
	ds_read_b128 v[70:73], v86 offset:1024
	ds_read_b128 v[78:81], v86 offset:2048
	ds_read_b128 v[86:89], v86 offset:3072
	ds_read_b128 v[146:149], v158
	ds_read_b128 v[150:153], v158 offset:1024
	ds_read_b128 v[154:157], v158 offset:2048
	ds_read_b128 v[158:161], v158 offset:3072
	s_add_u32 s10, s94, 0x80000
	s_addc_u32 s11, s95, 0
	s_mov_b32 m0, s59
	ds_read_b128 v[162:165], v236 offset:32768
	ds_read_b128 v[166:169], v236 offset:33792
	ds_read_b128 v[170:173], v236 offset:34816
	ds_read_b128 v[174:177], v236 offset:35840
	ds_read_b128 v[178:181], v236 offset:36864
	ds_read_b128 v[182:185], v236 offset:37888
	ds_read_b128 v[216:219], v236 offset:38912
	ds_read_b128 v[220:223], v236 offset:39936
	global_load_lds_dwordx4 v210, s[10:11]
	s_mov_b32 m0, s74
	s_nop 0
	global_load_lds_dwordx4 v208, s[10:11]
	s_waitcnt vmcnt(8)
	s_waitcnt lgkmcnt(0)
	s_barrier
	v_mfma_f32_16x16x32_bf16 v[142:145], v[66:69], v[162:165], v[142:145]
	v_mfma_f32_16x16x32_bf16 v[138:141], v[78:81], v[162:165], v[138:141]
	v_mfma_f32_16x16x32_bf16 v[126:129], v[66:69], v[170:173], v[126:129]
	v_mfma_f32_16x16x32_bf16 v[122:125], v[78:81], v[170:173], v[122:125]
	v_mfma_f32_16x16x32_bf16 v[110:113], v[66:69], v[178:181], v[110:113]
	v_mfma_f32_16x16x32_bf16 v[106:109], v[78:81], v[178:181], v[106:109]
	v_mfma_f32_16x16x32_bf16 v[94:97], v[66:69], v[216:219], v[94:97]
	v_mfma_f32_16x16x32_bf16 v[90:93], v[78:81], v[216:219], v[90:93]
	v_mfma_f32_16x16x32_bf16 v[142:145], v[70:73], v[166:169], v[142:145]
	v_mfma_f32_16x16x32_bf16 v[138:141], v[86:89], v[166:169], v[138:141]
	v_mfma_f32_16x16x32_bf16 v[126:129], v[70:73], v[174:177], v[126:129]
	v_mfma_f32_16x16x32_bf16 v[122:125], v[86:89], v[174:177], v[122:125]
	v_mfma_f32_16x16x32_bf16 v[110:113], v[70:73], v[182:185], v[110:113]
	v_mfma_f32_16x16x32_bf16 v[106:109], v[86:89], v[182:185], v[106:109]
	v_mfma_f32_16x16x32_bf16 v[94:97], v[70:73], v[220:223], v[94:97]
	v_mfma_f32_16x16x32_bf16 v[90:93], v[86:89], v[220:223], v[90:93]
	v_mfma_f32_16x16x32_bf16 v[134:137], v[146:149], v[162:165], v[134:137]
	v_mfma_f32_16x16x32_bf16 v[130:133], v[154:157], v[162:165], v[130:133]
	v_mfma_f32_16x16x32_bf16 v[118:121], v[146:149], v[170:173], v[118:121]
	v_mfma_f32_16x16x32_bf16 v[114:117], v[154:157], v[170:173], v[114:117]
	v_mfma_f32_16x16x32_bf16 v[102:105], v[146:149], v[178:181], v[102:105]
	v_mfma_f32_16x16x32_bf16 v[98:101], v[154:157], v[178:181], v[98:101]
	v_mfma_f32_16x16x32_bf16 v[82:85], v[146:149], v[216:219], v[82:85]
	v_mfma_f32_16x16x32_bf16 v[74:77], v[154:157], v[216:219], v[74:77]
	v_mfma_f32_16x16x32_bf16 v[134:137], v[150:153], v[166:169], v[134:137]
	v_mfma_f32_16x16x32_bf16 v[130:133], v[158:161], v[166:169], v[130:133]
	v_mfma_f32_16x16x32_bf16 v[118:121], v[150:153], v[174:177], v[118:121]
	v_mfma_f32_16x16x32_bf16 v[114:117], v[158:161], v[174:177], v[114:117]
	v_mfma_f32_16x16x32_bf16 v[102:105], v[150:153], v[182:185], v[102:105]
	v_mfma_f32_16x16x32_bf16 v[98:101], v[158:161], v[182:185], v[98:101]
	v_mfma_f32_16x16x32_bf16 v[82:85], v[150:153], v[220:223], v[82:85]
	v_mfma_f32_16x16x32_bf16 v[74:77], v[158:161], v[220:223], v[74:77]
	s_barrier
	s_add_i32 s9, s9, s25
	s_mov_b32 m0, s9
	ds_read_b128 v[162:165], v236 offset:49152
	ds_read_b128 v[166:169], v236 offset:50176
	ds_read_b128 v[170:173], v236 offset:51200
	ds_read_b128 v[174:177], v236 offset:52224
	ds_read_b128 v[178:181], v236 offset:53248
	ds_read_b128 v[182:185], v236 offset:54272
	ds_read_b128 v[216:219], v236 offset:55296
	ds_read_b128 v[220:223], v236 offset:56320
	s_add_u32 s100, s46, s60
	s_addc_u32 s101, s47, s61
	global_load_lds_dwordx4 v190, s[100:101]
	s_add_i32 m0, s9, 0x2000
	s_add_u32 s10, s46, 0x20080
	s_addc_u32 s11, s47, 0
	s_add_i32 s9, s12, s25
	global_load_lds_dwordx4 v206, s[100:101]
	s_mov_b32 m0, s9
	s_nop 0
	global_load_lds_dwordx4 v190, s[10:11]
	s_add_i32 m0, s9, 0x2000
	s_nop 0
	global_load_lds_dwordx4 v206, s[10:11]
	s_mov_b32 m0, s75
	s_add_u32 s100, s94, s60
	s_addc_u32 s101, s95, s61
	global_load_lds_dwordx4 v210, s[100:101]
	s_mov_b32 m0, s0
	s_nop 0
	global_load_lds_dwordx4 v208, s[100:101]
	s_waitcnt vmcnt(8)
	s_waitcnt lgkmcnt(0)
	s_barrier
	v_mfma_f32_16x16x32_bf16 v[62:65], v[66:69], v[162:165], v[62:65]
	v_mfma_f32_16x16x32_bf16 v[58:61], v[78:81], v[162:165], v[58:61]
	v_mfma_f32_16x16x32_bf16 v[46:49], v[66:69], v[170:173], v[46:49]
	v_mfma_f32_16x16x32_bf16 v[42:45], v[78:81], v[170:173], v[42:45]
	v_mfma_f32_16x16x32_bf16 v[30:33], v[66:69], v[178:181], v[30:33]
	v_mfma_f32_16x16x32_bf16 v[26:29], v[78:81], v[178:181], v[26:29]
	v_mfma_f32_16x16x32_bf16 v[14:17], v[66:69], v[216:219], v[14:17]
	v_mfma_f32_16x16x32_bf16 v[10:13], v[78:81], v[216:219], v[10:13]
	v_mfma_f32_16x16x32_bf16 v[62:65], v[70:73], v[166:169], v[62:65]
	v_mfma_f32_16x16x32_bf16 v[58:61], v[86:89], v[166:169], v[58:61]
	v_mfma_f32_16x16x32_bf16 v[46:49], v[70:73], v[174:177], v[46:49]
	v_mfma_f32_16x16x32_bf16 v[42:45], v[86:89], v[174:177], v[42:45]
	v_mfma_f32_16x16x32_bf16 v[30:33], v[70:73], v[182:185], v[30:33]
	v_mfma_f32_16x16x32_bf16 v[26:29], v[86:89], v[182:185], v[26:29]
	v_mfma_f32_16x16x32_bf16 v[14:17], v[70:73], v[220:223], v[14:17]
	v_mfma_f32_16x16x32_bf16 v[10:13], v[86:89], v[220:223], v[10:13]
	v_mfma_f32_16x16x32_bf16 v[54:57], v[146:149], v[162:165], v[54:57]
	v_mfma_f32_16x16x32_bf16 v[50:53], v[154:157], v[162:165], v[50:53]
	v_mfma_f32_16x16x32_bf16 v[38:41], v[146:149], v[170:173], v[38:41]
	v_mfma_f32_16x16x32_bf16 v[34:37], v[154:157], v[170:173], v[34:37]
	v_mfma_f32_16x16x32_bf16 v[22:25], v[146:149], v[178:181], v[22:25]
	v_mfma_f32_16x16x32_bf16 v[18:21], v[154:157], v[178:181], v[18:21]
	v_mfma_f32_16x16x32_bf16 v[6:9], v[146:149], v[216:219], v[6:9]
	v_mfma_f32_16x16x32_bf16 v[2:5], v[154:157], v[216:219], v[2:5]
	v_mfma_f32_16x16x32_bf16 v[54:57], v[150:153], v[166:169], v[54:57]
	v_mfma_f32_16x16x32_bf16 v[50:53], v[158:161], v[166:169], v[50:53]
	v_mfma_f32_16x16x32_bf16 v[38:41], v[150:153], v[174:177], v[38:41]
	v_mfma_f32_16x16x32_bf16 v[34:37], v[158:161], v[174:177], v[34:37]
	v_mfma_f32_16x16x32_bf16 v[22:25], v[150:153], v[182:185], v[22:25]
	v_mfma_f32_16x16x32_bf16 v[18:21], v[158:161], v[182:185], v[18:21]
	v_mfma_f32_16x16x32_bf16 v[6:9], v[150:153], v[220:223], v[6:9]
	v_mfma_f32_16x16x32_bf16 v[2:5], v[158:161], v[220:223], v[2:5]
	s_barrier
	s_add_i32 s8, s8, 2
	s_add_u32 s38, s38, 0x100
	s_addc_u32 s39, s39, 0
	s_add_u32 s6, s6, 0x100
	s_addc_u32 s7, s7, 0
	s_cmp_gt_u32 s8, 29
	s_cbranch_scc0 .LBB0_927
	s_and_b64 vcc, exec, s[70:71]
	s_cbranch_vccz .LBB0_930
	s_barrier

; #define PG8_STAGE(bufoff, gbase, voff) do { _Pragma("unroll") for (int _i = 0; _i < 2; ++_i) \
;         __builtin_amdgcn_global_load_lds((const unsigned*)((const char*)(gbase) + (voff)[_i]), (PG8_LAS unsigned*)(lds + (bufoff) + ldsw + _i * 8192), 16, 0, 0); } while (0)
; #define PG8_LDA(dst, b, h) do { _Pragma("unroll") for (int m = 0; m < 4; ++m) _Pragma("unroll") for (int k = 0; k < 2; ++k) dst[m][k] = *(const PG8_LAS bf16x8*)(lds + PG8_SA(b, h) + aoff + m * 2048 + k * 1024); } while (0)
; #define PG8_LDB(dst, b, h) do { _Pragma("unroll") for (int n = 0; n < 2; ++n) _Pragma("unroll") for (int k = 0; k < 2; ++k) dst[n][k] = *(const PG8_LAS bf16x8*)(lds + PG8_SB(b, h) + boff + n * 2048 + k * 1024); } while (0)
; #define PG8_MMA(ai, bj, At, Bt) do { __builtin_amdgcn_s_setprio(1); _Pragma("unroll") for (int m = 0; m < 4; ++m) _Pragma("unroll") for (int n = 0; n < 2; ++n) _Pragma("unroll") for (int k = 0; k < 2; ++k) \
;         acc[ai][bj][m][n] = __builtin_amdgcn_mfma_f32_16x16x32_bf16(Bt[n][k], At[m][k], acc[ai][bj][m][n], 0, 0, 0); __builtin_amdgcn_s_setprio(0); } while (0)
; #define PG8_WAIT_V(n) asm volatile("s_waitcnt vmcnt(" #n ")" ::: "memory")
; #define PG8_WAIT_L(n) asm volatile("s_waitcnt lgkmcnt(" #n ")" ::: "memory")
; template <class Epi, class Sched, bool ALIGN_EPI = false, bool SP2 = false>
; __device__ __forceinline__ void gemm_phase(PG8_LAS unsigned char* lds, const Gemm g, const Sched& S, const Epi& E) {
;     ...
;             const bool last = (t == nt - 2);
;             const char* a1 = cA + (size_t)(t + 1) * kstep;
;             const char* a2 = last ? nA : cA + (size_t)(t + 2) * kstep; const char* b2 = last ? nB : cB + (size_t)(t + 2) * kstep;
;             const char* a3 = a2 + kstep; const char* b3 = b2 + kstep;
;             if (last && has_next) S.a_ready(nxt);
;             if constexpr (SP2) {
;             PG8_LDB(B0, 0, 0); PG8_LDB(B1, 0, 1); PG8_SCHED; PG8_LDA(At, 0, 0); PG8_STAGE(PG8_SA(1, 1), a1 + hstep, voffA);
;             PG8_WAIT_V(8); PG8_WAIT_L(0); PG8_BAR; PG8_MMA(0, 0, At, B0); PG8_MMA(0, 1, At, B1); PG8_BAR; PG8_SCHED;
;             PG8_LDA(At, 0, 1); PG8_STAGE(PG8_SB(0, 0), b2, voffB); PG8_STAGE(PG8_SB(0, 1), b2 + hstepB, voffB); PG8_STAGE(PG8_SA(0, 0), a2, voffA);
;             PG8_WAIT_V(8); PG8_WAIT_L(0); PG8_BAR; PG8_MMA(1, 0, At, B0); PG8_MMA(1, 1, At, B1); PG8_BAR; PG8_SCHED;
.LBB0_1071:
	s_add_u32 s10, s38, 0xffe00080
	s_addc_u32 s11, s39, -1
	s_add_i32 s12, 0, 0x10000
	s_cmpk_eq_i32 s9, 0x7c
	s_cselect_b32 vcc_hi, s97, s11
	s_cselect_b32 vcc_lo, s4, s10
	s_cselect_b32 s47, s5, s8
	s_cselect_b32 s46, s6, s7
	s_add_i32 s13, 0, 0x14000
	v_add_u32_e32 v152, s12, v164
	v_add_u32_e32 v167, s13, v164
	ds_read_b128 v[130:133], v152
	ds_read_b128 v[134:137], v152 offset:1024
	ds_read_b128 v[138:141], v152 offset:2048
	ds_read_b128 v[152:155], v152 offset:3072
	ds_read_b128 v[156:159], v167
	ds_read_b128 v[160:163], v167 offset:1024
	ds_read_b128 v[168:171], v167 offset:2048
	ds_read_b128 v[172:175], v167 offset:3072
	s_add_i32 m0, s74, 0xc000
	ds_read_b128 v[176:179], v166
	ds_read_b128 v[180:183], v166 offset:1024
	ds_read_b128 v[206:209], v166 offset:2048
	ds_read_b128 v[210:213], v166 offset:3072
	ds_read_b128 v[214:217], v166 offset:4096
	ds_read_b128 v[218:221], v166 offset:5120
	ds_read_b128 v[236:239], v166 offset:6144
	ds_read_b128 v[240:243], v166 offset:7168
	global_load_lds_dwordx4 v148, s[38:39]
	s_add_i32 m0, s74, 0xe000
	s_nop 0
	global_load_lds_dwordx4 v150, s[38:39]
	s_waitcnt vmcnt(8)
	s_waitcnt lgkmcnt(0)
	s_barrier
	v_mfma_f32_16x16x32_bf16 v[126:129], v[130:133], v[176:179], v[126:129]
	v_mfma_f32_16x16x32_bf16 v[122:125], v[138:141], v[176:179], v[122:125]
	v_mfma_f32_16x16x32_bf16 v[110:113], v[130:133], v[206:209], v[110:113]
	v_mfma_f32_16x16x32_bf16 v[106:109], v[138:141], v[206:209], v[106:109]
	v_mfma_f32_16x16x32_bf16 v[94:97], v[130:133], v[214:217], v[94:97]
	v_mfma_f32_16x16x32_bf16 v[90:93], v[138:141], v[214:217], v[90:93]
	v_mfma_f32_16x16x32_bf16 v[78:81], v[130:133], v[236:239], v[78:81]
	v_mfma_f32_16x16x32_bf16 v[74:77], v[138:141], v[236:239], v[74:77]
	v_mfma_f32_16x16x32_bf16 v[126:129], v[134:137], v[180:183], v[126:129]
	v_mfma_f32_16x16x32_bf16 v[122:125], v[152:155], v[180:183], v[122:125]
	v_mfma_f32_16x16x32_bf16 v[110:113], v[134:137], v[210:213], v[110:113]
	v_mfma_f32_16x16x32_bf16 v[106:109], v[152:155], v[210:213], v[106:109]
	v_mfma_f32_16x16x32_bf16 v[94:97], v[134:137], v[218:221], v[94:97]
	v_mfma_f32_16x16x32_bf16 v[90:93], v[152:155], v[218:221], v[90:93]
	v_mfma_f32_16x16x32_bf16 v[78:81], v[134:137], v[240:243], v[78:81]
	v_mfma_f32_16x16x32_bf16 v[74:77], v[152:155], v[240:243], v[74:77]
	v_mfma_f32_16x16x32_bf16 v[118:121], v[156:159], v[176:179], v[118:121]
	v_mfma_f32_16x16x32_bf16 v[114:117], v[168:171], v[176:179], v[114:117]
	v_mfma_f32_16x16x32_bf16 v[102:105], v[156:159], v[206:209], v[102:105]
	v_mfma_f32_16x16x32_bf16 v[98:101], v[168:171], v[206:209], v[98:101]
	v_mfma_f32_16x16x32_bf16 v[86:89], v[156:159], v[214:217], v[86:89]
	v_mfma_f32_16x16x32_bf16 v[82:85], v[168:171], v[214:217], v[82:85]
	v_mfma_f32_16x16x32_bf16 v[70:73], v[156:159], v[236:239], v[70:73]
	v_mfma_f32_16x16x32_bf16 v[66:69], v[168:171], v[236:239], v[66:69]
	v_mfma_f32_16x16x32_bf16 v[118:121], v[160:163], v[180:183], v[118:121]
	v_mfma_f32_16x16x32_bf16 v[114:117], v[172:175], v[180:183], v[114:117]
	v_mfma_f32_16x16x32_bf16 v[102:105], v[160:163], v[210:213], v[102:105]
	v_mfma_f32_16x16x32_bf16 v[98:101], v[172:175], v[210:213], v[98:101]
	v_mfma_f32_16x16x32_bf16 v[86:89], v[160:163], v[218:221], v[86:89]
	v_mfma_f32_16x16x32_bf16 v[82:85], v[172:175], v[218:221], v[82:85]
	v_mfma_f32_16x16x32_bf16 v[70:73], v[160:163], v[240:243], v[70:73]
	v_mfma_f32_16x16x32_bf16 v[66:69], v[172:175], v[240:243], v[66:69]
	s_barrier
	s_add_i32 s10, s12, s67
	s_mov_b32 m0, s10
	ds_read_b128 v[176:179], v166 offset:16384
	ds_read_b128 v[180:183], v166 offset:17408
	ds_read_b128 v[206:209], v166 offset:18432
	ds_read_b128 v[210:213], v166 offset:19456
	ds_read_b128 v[214:217], v166 offset:20480
	ds_read_b128 v[218:221], v166 offset:21504
	ds_read_b128 v[236:239], v166 offset:22528
	ds_read_b128 v[240:243], v166 offset:23552
	global_load_lds_dwordx4 v146, s[46:47]
	s_add_i32 m0, s10, 0x2000
	s_add_u32 s10, s46, 0x80000
	s_addc_u32 s11, s47, 0
	s_add_i32 s12, s13, s67
	global_load_lds_dwordx4 v142, s[46:47]
	s_mov_b32 m0, s12
	s_nop 0
	global_load_lds_dwordx4 v146, s[10:11]
	s_add_i32 m0, s12, 0x2000
	s_nop 0
	global_load_lds_dwordx4 v142, s[10:11]
	s_mov_b32 m0, s74
	s_nop 0
	global_load_lds_dwordx4 v190, vcc
	s_mov_b32 m0, s75
	s_nop 0
	global_load_lds_dwordx4 v144, vcc
	s_waitcnt vmcnt(8)
	s_waitcnt lgkmcnt(0)
	s_barrier
	v_mfma_f32_16x16x32_bf16 v[62:65], v[130:133], v[176:179], v[62:65]
	v_mfma_f32_16x16x32_bf16 v[58:61], v[138:141], v[176:179], v[58:61]
	v_mfma_f32_16x16x32_bf16 v[46:49], v[130:133], v[206:209], v[46:49]
	v_mfma_f32_16x16x32_bf16 v[42:45], v[138:141], v[206:209], v[42:45]
	v_mfma_f32_16x16x32_bf16 v[30:33], v[130:133], v[214:217], v[30:33]
	v_mfma_f32_16x16x32_bf16 v[26:29], v[138:141], v[214:217], v[26:29]
	v_mfma_f32_16x16x32_bf16 v[14:17], v[130:133], v[236:239], v[14:17]
	v_mfma_f32_16x16x32_bf16 v[10:13], v[138:141], v[236:239], v[10:13]
	v_mfma_f32_16x16x32_bf16 v[62:65], v[134:137], v[180:183], v[62:65]
	v_mfma_f32_16x16x32_bf16 v[58:61], v[152:155], v[180:183], v[58:61]
	v_mfma_f32_16x16x32_bf16 v[46:49], v[134:137], v[210:213], v[46:49]
	v_mfma_f32_16x16x32_bf16 v[42:45], v[152:155], v[210:213], v[42:45]
	v_mfma_f32_16x16x32_bf16 v[30:33], v[134:137], v[218:221], v[30:33]
	v_mfma_f32_16x16x32_bf16 v[26:29], v[152:155], v[218:221], v[26:29]
	v_mfma_f32_16x16x32_bf16 v[14:17], v[134:137], v[240:243], v[14:17]
	v_mfma_f32_16x16x32_bf16 v[10:13], v[152:155], v[240:243], v[10:13]
	v_mfma_f32_16x16x32_bf16 v[54:57], v[156:159], v[176:179], v[54:57]
	v_mfma_f32_16x16x32_bf16 v[50:53], v[168:171], v[176:179], v[50:53]
	v_mfma_f32_16x16x32_bf16 v[38:41], v[156:159], v[206:209], v[38:41]
	v_mfma_f32_16x16x32_bf16 v[34:37], v[168:171], v[206:209], v[34:37]
	v_mfma_f32_16x16x32_bf16 v[22:25], v[156:159], v[214:217], v[22:25]
	v_mfma_f32_16x16x32_bf16 v[18:21], v[168:171], v[214:217], v[18:21]
	v_mfma_f32_16x16x32_bf16 v[6:9], v[156:159], v[236:239], v[6:9]
	v_mfma_f32_16x16x32_bf16 v[2:5], v[168:171], v[236:239], v[2:5]
	v_mfma_f32_16x16x32_bf16 v[54:57], v[160:163], v[180:183], v[54:57]
	v_mfma_f32_16x16x32_bf16 v[50:53], v[172:175], v[180:183], v[50:53]
	v_mfma_f32_16x16x32_bf16 v[38:41], v[160:163], v[210:213], v[38:41]
	v_mfma_f32_16x16x32_bf16 v[34:37], v[172:175], v[210:213], v[34:37]
	v_mfma_f32_16x16x32_bf16 v[22:25], v[160:163], v[218:221], v[22:25]
	v_mfma_f32_16x16x32_bf16 v[18:21], v[172:175], v[218:221], v[18:21]
	v_mfma_f32_16x16x32_bf16 v[6:9], v[160:163], v[240:243], v[6:9]
	v_mfma_f32_16x16x32_bf16 v[2:5], v[172:175], v[240:243], v[2:5]
	s_barrier
; #define PG8_STAGE(bufoff, gbase, voff) do { _Pragma("unroll") for (int _i = 0; _i < 2; ++_i) \
;         __builtin_amdgcn_global_load_lds((const unsigned*)((const char*)(gbase) + (voff)[_i]), (PG8_LAS unsigned*)(lds + (bufoff) + ldsw + _i * 8192), 16, 0, 0); } while (0)
; #define PG8_LDA(dst, b, h) do { _Pragma("unroll") for (int m = 0; m < 4; ++m) _Pragma("unroll") for (int k = 0; k < 2; ++k) dst[m][k] = *(const PG8_LAS bf16x8*)(lds + PG8_SA(b, h) + aoff + m * 2048 + k * 1024); } while (0)
; #define PG8_LDB(dst, b, h) do { _Pragma("unroll") for (int n = 0; n < 2; ++n) _Pragma("unroll") for (int k = 0; k < 2; ++k) dst[n][k] = *(const PG8_LAS bf16x8*)(lds + PG8_SB(b, h) + boff + n * 2048 + k * 1024); } while (0)
; #define PG8_MMA(ai, bj, At, Bt) do { __builtin_amdgcn_s_setprio(1); _Pragma("unroll") for (int m = 0; m < 4; ++m) _Pragma("unroll") for (int n = 0; n < 2; ++n) _Pragma("unroll") for (int k = 0; k < 2; ++k) \
;         acc[ai][bj][m][n] = __builtin_amdgcn_mfma_f32_16x16x32_bf16(Bt[n][k], At[m][k], acc[ai][bj][m][n], 0, 0, 0); __builtin_amdgcn_s_setprio(0); } while (0)
; #define PG8_WAIT_V(n) asm volatile("s_waitcnt vmcnt(" #n ")" ::: "memory")
; #define PG8_WAIT_L(n) asm volatile("s_waitcnt lgkmcnt(" #n ")" ::: "memory")
; #define PG8_BAR __builtin_amdgcn_s_barrier()
; #define PG8_SCHED __builtin_amdgcn_sched_barrier(0)
; template <class Epi, class Sched, bool ALIGN_EPI = false, bool SP2 = false>
; __device__ __forceinline__ void gemm_phase(PG8_LAS unsigned char* lds, const Gemm g, const Sched& S, const Epi& E) {
;     ...
;             PG8_LDB(B0, 1, 0); PG8_LDB(B1, 1, 1); PG8_SCHED; PG8_LDA(At, 1, 0); PG8_STAGE(PG8_SA(0, 1), a2 + hstep, voffA);
;             PG8_WAIT_V(8); PG8_WAIT_L(0); PG8_BAR; PG8_MMA(0, 0, At, B0); PG8_MMA(0, 1, At, B1); PG8_BAR; PG8_SCHED;
;             PG8_LDA(At, 1, 1); PG8_STAGE(PG8_SB(1, 0), b3, voffB); PG8_STAGE(PG8_SB(1, 1), b3 + hstepB, voffB); PG8_STAGE(PG8_SA(1, 0), a3, voffA);
;             PG8_WAIT_V(8); PG8_WAIT_L(0); PG8_BAR; PG8_MMA(1, 0, At, B0); PG8_MMA(1, 1, At, B1); PG8_BAR; PG8_SCHED;
	s_add_i32 s12, 0, 0x18000
	s_add_i32 s13, 0, 0x1c000
	v_add_u32_e32 v152, s12, v164
	v_add_u32_e32 v167, s13, v164
	ds_read_b128 v[130:133], v152
	ds_read_b128 v[134:137], v152 offset:1024
	ds_read_b128 v[138:141], v152 offset:2048
	ds_read_b128 v[152:155], v152 offset:3072
	ds_read_b128 v[156:159], v167
	ds_read_b128 v[160:163], v167 offset:1024
	ds_read_b128 v[168:171], v167 offset:2048
	ds_read_b128 v[172:175], v167 offset:3072
	s_add_u32 s10, vcc_lo, 0x200000
	s_addc_u32 s11, vcc_hi, 0
	s_mov_b32 m0, s86
	ds_read_b128 v[176:179], v166 offset:32768
	ds_read_b128 v[180:183], v166 offset:33792
	ds_read_b128 v[206:209], v166 offset:34816
	ds_read_b128 v[210:213], v166 offset:35840
	ds_read_b128 v[214:217], v166 offset:36864
	ds_read_b128 v[218:221], v166 offset:37888
	ds_read_b128 v[236:239], v166 offset:38912
	ds_read_b128 v[240:243], v166 offset:39936
	global_load_lds_dwordx4 v190, s[10:11]
	s_mov_b32 m0, s87
	s_nop 0
	global_load_lds_dwordx4 v144, s[10:11]
	s_waitcnt vmcnt(8)
	s_waitcnt lgkmcnt(0)
	s_barrier
	v_mfma_f32_16x16x32_bf16 v[126:129], v[130:133], v[176:179], v[126:129]
	v_mfma_f32_16x16x32_bf16 v[122:125], v[138:141], v[176:179], v[122:125]
	v_mfma_f32_16x16x32_bf16 v[110:113], v[130:133], v[206:209], v[110:113]
	v_mfma_f32_16x16x32_bf16 v[106:109], v[138:141], v[206:209], v[106:109]
	v_mfma_f32_16x16x32_bf16 v[94:97], v[130:133], v[214:217], v[94:97]
	v_mfma_f32_16x16x32_bf16 v[90:93], v[138:141], v[214:217], v[90:93]
	v_mfma_f32_16x16x32_bf16 v[78:81], v[130:133], v[236:239], v[78:81]
	v_mfma_f32_16x16x32_bf16 v[74:77], v[138:141], v[236:239], v[74:77]
	v_mfma_f32_16x16x32_bf16 v[126:129], v[134:137], v[180:183], v[126:129]
	v_mfma_f32_16x16x32_bf16 v[122:125], v[152:155], v[180:183], v[122:125]
	v_mfma_f32_16x16x32_bf16 v[110:113], v[134:137], v[210:213], v[110:113]
	v_mfma_f32_16x16x32_bf16 v[106:109], v[152:155], v[210:213], v[106:109]
	v_mfma_f32_16x16x32_bf16 v[94:97], v[134:137], v[218:221], v[94:97]
	v_mfma_f32_16x16x32_bf16 v[90:93], v[152:155], v[218:221], v[90:93]
	v_mfma_f32_16x16x32_bf16 v[78:81], v[134:137], v[240:243], v[78:81]
	v_mfma_f32_16x16x32_bf16 v[74:77], v[152:155], v[240:243], v[74:77]
	v_mfma_f32_16x16x32_bf16 v[118:121], v[156:159], v[176:179], v[118:121]
	v_mfma_f32_16x16x32_bf16 v[114:117], v[168:171], v[176:179], v[114:117]
	v_mfma_f32_16x16x32_bf16 v[102:105], v[156:159], v[206:209], v[102:105]
	v_mfma_f32_16x16x32_bf16 v[98:101], v[168:171], v[206:209], v[98:101]
	v_mfma_f32_16x16x32_bf16 v[86:89], v[156:159], v[214:217], v[86:89]
	v_mfma_f32_16x16x32_bf16 v[82:85], v[168:171], v[214:217], v[82:85]
	v_mfma_f32_16x16x32_bf16 v[70:73], v[156:159], v[236:239], v[70:73]
	v_mfma_f32_16x16x32_bf16 v[66:69], v[168:171], v[236:239], v[66:69]
	v_mfma_f32_16x16x32_bf16 v[118:121], v[160:163], v[180:183], v[118:121]
	v_mfma_f32_16x16x32_bf16 v[114:117], v[172:175], v[180:183], v[114:117]
	v_mfma_f32_16x16x32_bf16 v[102:105], v[160:163], v[210:213], v[102:105]
	v_mfma_f32_16x16x32_bf16 v[98:101], v[172:175], v[210:213], v[98:101]
	v_mfma_f32_16x16x32_bf16 v[86:89], v[160:163], v[218:221], v[86:89]
	v_mfma_f32_16x16x32_bf16 v[82:85], v[172:175], v[218:221], v[82:85]
	v_mfma_f32_16x16x32_bf16 v[70:73], v[160:163], v[240:243], v[70:73]
	v_mfma_f32_16x16x32_bf16 v[66:69], v[172:175], v[240:243], v[66:69]
	s_barrier
	s_add_i32 s10, s12, s67
	s_mov_b32 m0, s10
	ds_read_b128 v[176:179], v166 offset:49152
	ds_read_b128 v[180:183], v166 offset:50176
	ds_read_b128 v[206:209], v166 offset:51200
	ds_read_b128 v[210:213], v166 offset:52224
	ds_read_b128 v[214:217], v166 offset:53248
	ds_read_b128 v[218:221], v166 offset:54272
	ds_read_b128 v[236:239], v166 offset:55296
	ds_read_b128 v[240:243], v166 offset:56320
	s_add_u32 s100, s46, s60
	s_addc_u32 s101, s47, s61
	global_load_lds_dwordx4 v146, s[100:101]
	s_add_i32 m0, s10, 0x2000
	s_add_u32 s10, s46, 0x80080
	s_addc_u32 s11, s47, 0
	s_add_i32 s12, s13, s67
	global_load_lds_dwordx4 v142, s[100:101]
	s_mov_b32 m0, s12
	s_nop 0
	global_load_lds_dwordx4 v146, s[10:11]
	s_add_i32 m0, s12, 0x2000
	s_nop 0
	global_load_lds_dwordx4 v142, s[10:11]
	s_mov_b32 m0, s82
	s_add_u32 s100, vcc_lo, s60
	s_addc_u32 s101, vcc_hi, s61
	global_load_lds_dwordx4 v190, s[100:101]
	s_mov_b32 m0, s42
	s_nop 0
	global_load_lds_dwordx4 v144, s[100:101]
	s_waitcnt vmcnt(8)
	s_waitcnt lgkmcnt(0)
	s_barrier
	v_mfma_f32_16x16x32_bf16 v[62:65], v[130:133], v[176:179], v[62:65]
	v_mfma_f32_16x16x32_bf16 v[58:61], v[138:141], v[176:179], v[58:61]
	v_mfma_f32_16x16x32_bf16 v[46:49], v[130:133], v[206:209], v[46:49]
	v_mfma_f32_16x16x32_bf16 v[42:45], v[138:141], v[206:209], v[42:45]
	v_mfma_f32_16x16x32_bf16 v[30:33], v[130:133], v[214:217], v[30:33]
	v_mfma_f32_16x16x32_bf16 v[26:29], v[138:141], v[214:217], v[26:29]
	v_mfma_f32_16x16x32_bf16 v[14:17], v[130:133], v[236:239], v[14:17]
	v_mfma_f32_16x16x32_bf16 v[10:13], v[138:141], v[236:239], v[10:13]
	v_mfma_f32_16x16x32_bf16 v[62:65], v[134:137], v[180:183], v[62:65]
	v_mfma_f32_16x16x32_bf16 v[58:61], v[152:155], v[180:183], v[58:61]
	v_mfma_f32_16x16x32_bf16 v[46:49], v[134:137], v[210:213], v[46:49]
	v_mfma_f32_16x16x32_bf16 v[42:45], v[152:155], v[210:213], v[42:45]
	v_mfma_f32_16x16x32_bf16 v[30:33], v[134:137], v[218:221], v[30:33]
	v_mfma_f32_16x16x32_bf16 v[26:29], v[152:155], v[218:221], v[26:29]
	v_mfma_f32_16x16x32_bf16 v[14:17], v[134:137], v[240:243], v[14:17]
	v_mfma_f32_16x16x32_bf16 v[10:13], v[152:155], v[240:243], v[10:13]
	v_mfma_f32_16x16x32_bf16 v[54:57], v[156:159], v[176:179], v[54:57]
	v_mfma_f32_16x16x32_bf16 v[50:53], v[168:171], v[176:179], v[50:53]
	v_mfma_f32_16x16x32_bf16 v[38:41], v[156:159], v[206:209], v[38:41]
	v_mfma_f32_16x16x32_bf16 v[34:37], v[168:171], v[206:209], v[34:37]
	v_mfma_f32_16x16x32_bf16 v[22:25], v[156:159], v[214:217], v[22:25]
	v_mfma_f32_16x16x32_bf16 v[18:21], v[168:171], v[214:217], v[18:21]
	v_mfma_f32_16x16x32_bf16 v[6:9], v[156:159], v[236:239], v[6:9]
	v_mfma_f32_16x16x32_bf16 v[2:5], v[168:171], v[236:239], v[2:5]
	v_mfma_f32_16x16x32_bf16 v[54:57], v[160:163], v[180:183], v[54:57]
	v_mfma_f32_16x16x32_bf16 v[50:53], v[172:175], v[180:183], v[50:53]
	v_mfma_f32_16x16x32_bf16 v[38:41], v[160:163], v[210:213], v[38:41]
	v_mfma_f32_16x16x32_bf16 v[34:37], v[172:175], v[210:213], v[34:37]
	v_mfma_f32_16x16x32_bf16 v[22:25], v[160:163], v[218:221], v[22:25]
	v_mfma_f32_16x16x32_bf16 v[18:21], v[172:175], v[218:221], v[18:21]
	v_mfma_f32_16x16x32_bf16 v[6:9], v[160:163], v[240:243], v[6:9]
	v_mfma_f32_16x16x32_bf16 v[2:5], v[172:175], v[240:243], v[2:5]
	s_barrier
	s_add_i32 s9, s9, 2
	s_add_u32 s38, s38, 0x100
	s_addc_u32 s39, s39, 0
	s_add_u32 s7, s7, 0x100
	s_addc_u32 s8, s8, 0
	s_cmpk_gt_u32 s9, 0x7d
	s_cbranch_scc0 .LBB0_1071
	s_and_b64 vcc, exec, s[72:73]
	s_cbranch_vccz .LBB0_1074
	s_barrier

; #define PG8_STAGE(bufoff, gbase, voff) do { _Pragma("unroll") for (int _i = 0; _i < 2; ++_i) \
;         __builtin_amdgcn_global_load_lds((const unsigned*)((const char*)(gbase) + (voff)[_i]), (PG8_LAS unsigned*)(lds + (bufoff) + ldsw + _i * 8192), 16, 0, 0); } while (0)
; #define PG8_LDA(dst, b, h) do { _Pragma("unroll") for (int m = 0; m < 4; ++m) _Pragma("unroll") for (int k = 0; k < 2; ++k) dst[m][k] = *(const PG8_LAS bf16x8*)(lds + PG8_SA(b, h) + aoff + m * 2048 + k * 1024); } while (0)
; #define PG8_LDB(dst, b, h) do { _Pragma("unroll") for (int n = 0; n < 2; ++n) _Pragma("unroll") for (int k = 0; k < 2; ++k) dst[n][k] = *(const PG8_LAS bf16x8*)(lds + PG8_SB(b, h) + boff + n * 2048 + k * 1024); } while (0)
; #define PG8_MMA(ai, bj, At, Bt) do { __builtin_amdgcn_s_setprio(1); _Pragma("unroll") for (int m = 0; m < 4; ++m) _Pragma("unroll") for (int n = 0; n < 2; ++n) _Pragma("unroll") for (int k = 0; k < 2; ++k) \
;         acc[ai][bj][m][n] = __builtin_amdgcn_mfma_f32_16x16x32_bf16(Bt[n][k], At[m][k], acc[ai][bj][m][n], 0, 0, 0); __builtin_amdgcn_s_setprio(0); } while (0)
; #define PG8_WAIT_V(n) asm volatile("s_waitcnt vmcnt(" #n ")" ::: "memory")
; #define PG8_WAIT_L(n) asm volatile("s_waitcnt lgkmcnt(" #n ")" ::: "memory")
; template <class Epi, class Sched, bool ALIGN_EPI = false, bool SP2 = false>
; __device__ __forceinline__ void gemm_phase(PG8_LAS unsigned char* lds, const Gemm g, const Sched& S, const Epi& E) {
;     ...
;             const bool last = (t == nt - 2);
;             const char* a1 = cA + (size_t)(t + 1) * kstep;
;             const char* a2 = last ? nA : cA + (size_t)(t + 2) * kstep; const char* b2 = last ? nB : cB + (size_t)(t + 2) * kstep;
;             const char* a3 = a2 + kstep; const char* b3 = b2 + kstep;
;             if (last && has_next) S.a_ready(nxt);
;             if constexpr (SP2) {
;             PG8_LDB(B0, 0, 0); PG8_LDB(B1, 0, 1); PG8_SCHED; PG8_LDA(At, 0, 0); PG8_STAGE(PG8_SA(1, 1), a1 + hstep, voffA);
;             PG8_WAIT_V(8); PG8_WAIT_L(0); PG8_BAR; PG8_MMA(0, 0, At, B0); PG8_MMA(0, 1, At, B1); PG8_BAR; PG8_SCHED;
;             PG8_LDA(At, 0, 1); PG8_STAGE(PG8_SB(0, 0), b2, voffB); PG8_STAGE(PG8_SB(0, 1), b2 + hstepB, voffB); PG8_STAGE(PG8_SA(0, 0), a2, voffA);
;             PG8_WAIT_V(8); PG8_WAIT_L(0); PG8_BAR; PG8_MMA(1, 0, At, B0); PG8_MMA(1, 1, At, B1); PG8_BAR; PG8_SCHED;
.LBB0_1233:
	s_add_u32 s9, s68, s80
	s_addc_u32 s10, s69, s81
	s_add_u32 s9, s9, 0x100
	s_addc_u32 s10, s10, 0
	s_add_u32 s11, s36, s80
	s_addc_u32 s12, s37, s81
	s_add_i32 s13, 0, 0x10000
	s_cmpk_eq_i32 s80, 0xf00
	s_cselect_b32 s93, s4, s10
	s_cselect_b32 s92, s5, s9
	v_add_u32_e32 v144, s13, v145
	s_cselect_b32 s85, s6, s12
	s_cselect_b32 s84, s7, s11
	s_add_i32 s9, 0, 0x14000
	ds_read_b128 v[152:155], v144
	ds_read_b128 v[156:159], v144 offset:1024
	ds_read_b128 v[160:163], v144 offset:2048
	ds_read_b128 v[164:167], v144 offset:3072
	v_add_u32_e32 v144, s9, v145
	ds_read_b128 v[168:171], v144
	ds_read_b128 v[172:175], v144 offset:1024
	ds_read_b128 v[176:179], v144 offset:2048
	ds_read_b128 v[180:183], v144 offset:3072
	v_lshl_add_u64 v[184:185], v[140:141], 0, s[80:81]
	s_add_i32 m0, s51, 0xc000
	ds_read_b128 v[206:209], v151
	ds_read_b128 v[210:213], v151 offset:1024
	ds_read_b128 v[214:217], v151 offset:2048
	ds_read_b128 v[218:221], v151 offset:3072
	ds_read_b128 v[236:239], v151 offset:4096
	ds_read_b128 v[240:243], v151 offset:5120
	ds_read_b128 v[244:247], v151 offset:6144
	ds_read_b128 v[194:197], v151 offset:7168
	global_load_lds_dwordx4 v[184:185], off
	s_add_i32 m0, s51, 0xe000
	v_lshl_add_u64 v[184:185], v[142:143], 0, s[80:81]
	global_load_lds_dwordx4 v[184:185], off
	s_waitcnt vmcnt(8)
	s_waitcnt lgkmcnt(0)
	s_barrier
	v_mfma_f32_16x16x32_bf16 v[126:129], v[152:155], v[206:209], v[126:129]
	v_mfma_f32_16x16x32_bf16 v[122:125], v[160:163], v[206:209], v[122:125]
	v_mfma_f32_16x16x32_bf16 v[118:121], v[152:155], v[214:217], v[118:121]
	v_mfma_f32_16x16x32_bf16 v[114:117], v[160:163], v[214:217], v[114:117]
	v_mfma_f32_16x16x32_bf16 v[110:113], v[152:155], v[236:239], v[110:113]
	v_mfma_f32_16x16x32_bf16 v[106:109], v[160:163], v[236:239], v[106:109]
	v_mfma_f32_16x16x32_bf16 v[102:105], v[152:155], v[244:247], v[102:105]
	v_mfma_f32_16x16x32_bf16 v[98:101], v[160:163], v[244:247], v[98:101]
	v_mfma_f32_16x16x32_bf16 v[126:129], v[156:159], v[210:213], v[126:129]
	v_mfma_f32_16x16x32_bf16 v[122:125], v[164:167], v[210:213], v[122:125]
	v_mfma_f32_16x16x32_bf16 v[118:121], v[156:159], v[218:221], v[118:121]
	v_mfma_f32_16x16x32_bf16 v[114:117], v[164:167], v[218:221], v[114:117]
	v_mfma_f32_16x16x32_bf16 v[110:113], v[156:159], v[240:243], v[110:113]
	v_mfma_f32_16x16x32_bf16 v[106:109], v[164:167], v[240:243], v[106:109]
	v_mfma_f32_16x16x32_bf16 v[102:105], v[156:159], v[194:197], v[102:105]
	v_mfma_f32_16x16x32_bf16 v[98:101], v[164:167], v[194:197], v[98:101]
	v_mfma_f32_16x16x32_bf16 v[94:97], v[168:171], v[206:209], v[94:97]
	v_mfma_f32_16x16x32_bf16 v[90:93], v[176:179], v[206:209], v[90:93]
	v_mfma_f32_16x16x32_bf16 v[86:89], v[168:171], v[214:217], v[86:89]
	v_mfma_f32_16x16x32_bf16 v[82:85], v[176:179], v[214:217], v[82:85]
	v_mfma_f32_16x16x32_bf16 v[78:81], v[168:171], v[236:239], v[78:81]
	v_mfma_f32_16x16x32_bf16 v[74:77], v[176:179], v[236:239], v[74:77]
	v_mfma_f32_16x16x32_bf16 v[70:73], v[168:171], v[244:247], v[70:73]
	v_mfma_f32_16x16x32_bf16 v[66:69], v[176:179], v[244:247], v[66:69]
	v_mfma_f32_16x16x32_bf16 v[94:97], v[172:175], v[210:213], v[94:97]
	v_mfma_f32_16x16x32_bf16 v[90:93], v[180:183], v[210:213], v[90:93]
	v_mfma_f32_16x16x32_bf16 v[86:89], v[172:175], v[218:221], v[86:89]
	v_mfma_f32_16x16x32_bf16 v[82:85], v[180:183], v[218:221], v[82:85]
	v_mfma_f32_16x16x32_bf16 v[78:81], v[172:175], v[240:243], v[78:81]
	v_mfma_f32_16x16x32_bf16 v[74:77], v[180:183], v[240:243], v[74:77]
	v_mfma_f32_16x16x32_bf16 v[70:73], v[172:175], v[194:197], v[70:73]
	v_mfma_f32_16x16x32_bf16 v[66:69], v[180:183], v[194:197], v[66:69]
	s_barrier
	s_add_i32 s10, s13, s42
	s_mov_b32 m0, s10
	ds_read_b128 v[194:197], v151 offset:16384
	ds_read_b128 v[206:209], v151 offset:17408
	ds_read_b128 v[210:213], v151 offset:18432
	ds_read_b128 v[214:217], v151 offset:19456
	ds_read_b128 v[218:221], v151 offset:20480
	ds_read_b128 v[236:239], v151 offset:21504
	ds_read_b128 v[240:243], v151 offset:22528
	ds_read_b128 v[244:247], v151 offset:23552
	global_load_lds_dwordx4 v130, s[84:85]
	s_add_i32 m0, s10, 0x2000
	s_add_u32 s10, s84, 0x20000
	s_addc_u32 s11, s85, 0
	s_add_i32 s9, s9, s42
	global_load_lds_dwordx4 v134, s[84:85]
	s_mov_b32 m0, s9
	s_nop 0
	global_load_lds_dwordx4 v130, s[10:11]
	s_add_i32 m0, s9, 0x2000
	s_nop 0
	global_load_lds_dwordx4 v134, s[10:11]
	s_mov_b32 m0, s51
	s_nop 0
	global_load_lds_dwordx4 v190, s[92:93]
	s_mov_b32 m0, s67
	s_nop 0
	global_load_lds_dwordx4 v132, s[92:93]
	s_waitcnt vmcnt(8)
	s_waitcnt lgkmcnt(0)
	s_barrier
; #define PG8_STAGE(bufoff, gbase, voff) do { _Pragma("unroll") for (int _i = 0; _i < 2; ++_i) \
;         __builtin_amdgcn_global_load_lds((const unsigned*)((const char*)(gbase) + (voff)[_i]), (PG8_LAS unsigned*)(lds + (bufoff) + ldsw + _i * 8192), 16, 0, 0); } while (0)
; #define PG8_LDA(dst, b, h) do { _Pragma("unroll") for (int m = 0; m < 4; ++m) _Pragma("unroll") for (int k = 0; k < 2; ++k) dst[m][k] = *(const PG8_LAS bf16x8*)(lds + PG8_SA(b, h) + aoff + m * 2048 + k * 1024); } while (0)
; #define PG8_LDB(dst, b, h) do { _Pragma("unroll") for (int n = 0; n < 2; ++n) _Pragma("unroll") for (int k = 0; k < 2; ++k) dst[n][k] = *(const PG8_LAS bf16x8*)(lds + PG8_SB(b, h) + boff + n * 2048 + k * 1024); } while (0)
; #define PG8_MMA(ai, bj, At, Bt) do { __builtin_amdgcn_s_setprio(1); _Pragma("unroll") for (int m = 0; m < 4; ++m) _Pragma("unroll") for (int n = 0; n < 2; ++n) _Pragma("unroll") for (int k = 0; k < 2; ++k) \
;         acc[ai][bj][m][n] = __builtin_amdgcn_mfma_f32_16x16x32_bf16(Bt[n][k], At[m][k], acc[ai][bj][m][n], 0, 0, 0); __builtin_amdgcn_s_setprio(0); } while (0)
; #define PG8_WAIT_V(n) asm volatile("s_waitcnt vmcnt(" #n ")" ::: "memory")
; #define PG8_WAIT_L(n) asm volatile("s_waitcnt lgkmcnt(" #n ")" ::: "memory")
; #define PG8_BAR __builtin_amdgcn_s_barrier()
; #define PG8_SCHED __builtin_amdgcn_sched_barrier(0)
; template <class Epi, class Sched, bool ALIGN_EPI = false, bool SP2 = false>
; __device__ __forceinline__ void gemm_phase(PG8_LAS unsigned char* lds, const Gemm g, const Sched& S, const Epi& E) {
;     ...
;             PG8_WAIT_V(8); PG8_WAIT_L(0); PG8_BAR; PG8_MMA(0, 0, At, B0); PG8_MMA(0, 1, At, B1); PG8_BAR; PG8_SCHED;
;             PG8_LDA(At, 0, 1); PG8_STAGE(PG8_SB(0, 0), b2, voffB); PG8_STAGE(PG8_SB(0, 1), b2 + hstepB, voffB); PG8_STAGE(PG8_SA(0, 0), a2, voffA);
;             PG8_WAIT_V(8); PG8_WAIT_L(0); PG8_BAR; PG8_MMA(1, 0, At, B0); PG8_MMA(1, 1, At, B1); PG8_BAR; PG8_SCHED;
;             PG8_LDB(B0, 1, 0); PG8_LDB(B1, 1, 1); PG8_SCHED; PG8_LDA(At, 1, 0); PG8_STAGE(PG8_SA(0, 1), a2 + hstep, voffA);
;             PG8_WAIT_V(8); PG8_WAIT_L(0); PG8_BAR; PG8_MMA(0, 0, At, B0); PG8_MMA(0, 1, At, B1); PG8_BAR; PG8_SCHED;
	v_mfma_f32_16x16x32_bf16 v[62:65], v[152:155], v[194:197], v[62:65]
	v_mfma_f32_16x16x32_bf16 v[58:61], v[160:163], v[194:197], v[58:61]
	v_mfma_f32_16x16x32_bf16 v[54:57], v[152:155], v[210:213], v[54:57]
	v_mfma_f32_16x16x32_bf16 v[50:53], v[160:163], v[210:213], v[50:53]
	v_mfma_f32_16x16x32_bf16 v[46:49], v[152:155], v[218:221], v[46:49]
	v_mfma_f32_16x16x32_bf16 v[42:45], v[160:163], v[218:221], v[42:45]
	v_mfma_f32_16x16x32_bf16 v[38:41], v[152:155], v[240:243], v[38:41]
	v_mfma_f32_16x16x32_bf16 v[34:37], v[160:163], v[240:243], v[34:37]
	v_mfma_f32_16x16x32_bf16 v[62:65], v[156:159], v[206:209], v[62:65]
	v_mfma_f32_16x16x32_bf16 v[58:61], v[164:167], v[206:209], v[58:61]
	v_mfma_f32_16x16x32_bf16 v[54:57], v[156:159], v[214:217], v[54:57]
	v_mfma_f32_16x16x32_bf16 v[50:53], v[164:167], v[214:217], v[50:53]
	v_mfma_f32_16x16x32_bf16 v[46:49], v[156:159], v[236:239], v[46:49]
	v_mfma_f32_16x16x32_bf16 v[42:45], v[164:167], v[236:239], v[42:45]
	v_mfma_f32_16x16x32_bf16 v[38:41], v[156:159], v[244:247], v[38:41]
	v_mfma_f32_16x16x32_bf16 v[34:37], v[164:167], v[244:247], v[34:37]
	v_mfma_f32_16x16x32_bf16 v[30:33], v[168:171], v[194:197], v[30:33]
	v_mfma_f32_16x16x32_bf16 v[26:29], v[176:179], v[194:197], v[26:29]
	v_mfma_f32_16x16x32_bf16 v[22:25], v[168:171], v[210:213], v[22:25]
	v_mfma_f32_16x16x32_bf16 v[18:21], v[176:179], v[210:213], v[18:21]
	v_mfma_f32_16x16x32_bf16 v[14:17], v[168:171], v[218:221], v[14:17]
	v_mfma_f32_16x16x32_bf16 v[10:13], v[176:179], v[218:221], v[10:13]
	v_mfma_f32_16x16x32_bf16 v[6:9], v[168:171], v[240:243], v[6:9]
	v_mfma_f32_16x16x32_bf16 v[2:5], v[176:179], v[240:243], v[2:5]
	v_mfma_f32_16x16x32_bf16 v[30:33], v[172:175], v[206:209], v[30:33]
	v_mfma_f32_16x16x32_bf16 v[26:29], v[180:183], v[206:209], v[26:29]
	v_mfma_f32_16x16x32_bf16 v[22:25], v[172:175], v[214:217], v[22:25]
	v_mfma_f32_16x16x32_bf16 v[18:21], v[180:183], v[214:217], v[18:21]
	v_mfma_f32_16x16x32_bf16 v[14:17], v[172:175], v[236:239], v[14:17]
	v_mfma_f32_16x16x32_bf16 v[10:13], v[180:183], v[236:239], v[10:13]
	v_mfma_f32_16x16x32_bf16 v[6:9], v[172:175], v[244:247], v[6:9]
	v_mfma_f32_16x16x32_bf16 v[2:5], v[180:183], v[244:247], v[2:5]
	s_barrier
	s_add_i32 s9, 0, 0x18000
	v_add_u32_e32 v144, s9, v145
	s_add_i32 s12, 0, 0x1c000
	ds_read_b128 v[152:155], v144
	ds_read_b128 v[156:159], v144 offset:1024
	ds_read_b128 v[160:163], v144 offset:2048
	ds_read_b128 v[164:167], v144 offset:3072
	v_add_u32_e32 v144, s12, v145
	ds_read_b128 v[168:171], v144
	ds_read_b128 v[172:175], v144 offset:1024
	ds_read_b128 v[176:179], v144 offset:2048
	ds_read_b128 v[180:183], v144 offset:3072
	s_add_u32 s10, s92, 0x80000
	s_addc_u32 s11, s93, 0
	s_mov_b32 m0, s74
	ds_read_b128 v[194:197], v151 offset:32768
	ds_read_b128 v[206:209], v151 offset:33792
	ds_read_b128 v[210:213], v151 offset:34816
	ds_read_b128 v[214:217], v151 offset:35840
	ds_read_b128 v[218:221], v151 offset:36864
	ds_read_b128 v[236:239], v151 offset:37888
	ds_read_b128 v[240:243], v151 offset:38912
	ds_read_b128 v[244:247], v151 offset:39936
	global_load_lds_dwordx4 v190, s[10:11]
	s_mov_b32 m0, s75
	s_nop 0
	global_load_lds_dwordx4 v132, s[10:11]
	s_waitcnt vmcnt(8)
	s_waitcnt lgkmcnt(0)
	s_barrier
	v_mfma_f32_16x16x32_bf16 v[126:129], v[152:155], v[194:197], v[126:129]
	v_mfma_f32_16x16x32_bf16 v[122:125], v[160:163], v[194:197], v[122:125]
	v_mfma_f32_16x16x32_bf16 v[118:121], v[152:155], v[210:213], v[118:121]
	v_mfma_f32_16x16x32_bf16 v[114:117], v[160:163], v[210:213], v[114:117]
	v_mfma_f32_16x16x32_bf16 v[110:113], v[152:155], v[218:221], v[110:113]
	v_mfma_f32_16x16x32_bf16 v[106:109], v[160:163], v[218:221], v[106:109]
	v_mfma_f32_16x16x32_bf16 v[102:105], v[152:155], v[240:243], v[102:105]
	v_mfma_f32_16x16x32_bf16 v[98:101], v[160:163], v[240:243], v[98:101]
	v_mfma_f32_16x16x32_bf16 v[126:129], v[156:159], v[206:209], v[126:129]
	v_mfma_f32_16x16x32_bf16 v[122:125], v[164:167], v[206:209], v[122:125]
	v_mfma_f32_16x16x32_bf16 v[118:121], v[156:159], v[214:217], v[118:121]
	v_mfma_f32_16x16x32_bf16 v[114:117], v[164:167], v[214:217], v[114:117]
	v_mfma_f32_16x16x32_bf16 v[110:113], v[156:159], v[236:239], v[110:113]
	v_mfma_f32_16x16x32_bf16 v[106:109], v[164:167], v[236:239], v[106:109]
	v_mfma_f32_16x16x32_bf16 v[102:105], v[156:159], v[244:247], v[102:105]
	v_mfma_f32_16x16x32_bf16 v[98:101], v[164:167], v[244:247], v[98:101]
	v_mfma_f32_16x16x32_bf16 v[94:97], v[168:171], v[194:197], v[94:97]
	v_mfma_f32_16x16x32_bf16 v[90:93], v[176:179], v[194:197], v[90:93]
	v_mfma_f32_16x16x32_bf16 v[86:89], v[168:171], v[210:213], v[86:89]
	v_mfma_f32_16x16x32_bf16 v[82:85], v[176:179], v[210:213], v[82:85]
	v_mfma_f32_16x16x32_bf16 v[78:81], v[168:171], v[218:221], v[78:81]
	v_mfma_f32_16x16x32_bf16 v[74:77], v[176:179], v[218:221], v[74:77]
	v_mfma_f32_16x16x32_bf16 v[70:73], v[168:171], v[240:243], v[70:73]
	v_mfma_f32_16x16x32_bf16 v[66:69], v[176:179], v[240:243], v[66:69]
	v_mfma_f32_16x16x32_bf16 v[94:97], v[172:175], v[206:209], v[94:97]
	v_mfma_f32_16x16x32_bf16 v[90:93], v[180:183], v[206:209], v[90:93]
	v_mfma_f32_16x16x32_bf16 v[86:89], v[172:175], v[214:217], v[86:89]
	v_mfma_f32_16x16x32_bf16 v[82:85], v[180:183], v[214:217], v[82:85]
	v_mfma_f32_16x16x32_bf16 v[78:81], v[172:175], v[236:239], v[78:81]
	v_mfma_f32_16x16x32_bf16 v[74:77], v[180:183], v[236:239], v[74:77]
	v_mfma_f32_16x16x32_bf16 v[70:73], v[172:175], v[244:247], v[70:73]
	v_mfma_f32_16x16x32_bf16 v[66:69], v[180:183], v[244:247], v[66:69]
	s_barrier
; #define PG8_STAGE(bufoff, gbase, voff) do { _Pragma("unroll") for (int _i = 0; _i < 2; ++_i) \
;         __builtin_amdgcn_global_load_lds((const unsigned*)((const char*)(gbase) + (voff)[_i]), (PG8_LAS unsigned*)(lds + (bufoff) + ldsw + _i * 8192), 16, 0, 0); } while (0)
; #define PG8_LDA(dst, b, h) do { _Pragma("unroll") for (int m = 0; m < 4; ++m) _Pragma("unroll") for (int k = 0; k < 2; ++k) dst[m][k] = *(const PG8_LAS bf16x8*)(lds + PG8_SA(b, h) + aoff + m * 2048 + k * 1024); } while (0)
; #define PG8_MMA(ai, bj, At, Bt) do { __builtin_amdgcn_s_setprio(1); _Pragma("unroll") for (int m = 0; m < 4; ++m) _Pragma("unroll") for (int n = 0; n < 2; ++n) _Pragma("unroll") for (int k = 0; k < 2; ++k) \
;         acc[ai][bj][m][n] = __builtin_amdgcn_mfma_f32_16x16x32_bf16(Bt[n][k], At[m][k], acc[ai][bj][m][n], 0, 0, 0); __builtin_amdgcn_s_setprio(0); } while (0)
; #define PG8_WAIT_V(n) asm volatile("s_waitcnt vmcnt(" #n ")" ::: "memory")
; #define PG8_WAIT_L(n) asm volatile("s_waitcnt lgkmcnt(" #n ")" ::: "memory")
; #define PG8_BAR __builtin_amdgcn_s_barrier()
; #define PG8_SCHED __builtin_amdgcn_sched_barrier(0)
; template <class Epi, class Sched, bool ALIGN_EPI = false, bool SP2 = false>
; __device__ __forceinline__ void gemm_phase(PG8_LAS unsigned char* lds, const Gemm g, const Sched& S, const Epi& E) {
;     ...
;             PG8_LDA(At, 1, 1); PG8_STAGE(PG8_SB(1, 0), b3, voffB); PG8_STAGE(PG8_SB(1, 1), b3 + hstepB, voffB); PG8_STAGE(PG8_SA(1, 0), a3, voffA);
;             PG8_WAIT_V(8); PG8_WAIT_L(0); PG8_BAR; PG8_MMA(1, 0, At, B0); PG8_MMA(1, 1, At, B1); PG8_BAR; PG8_SCHED;
	s_add_i32 s9, s9, s42
	s_mov_b32 m0, s9
	ds_read_b128 v[194:197], v151 offset:49152
	ds_read_b128 v[206:209], v151 offset:50176
	ds_read_b128 v[210:213], v151 offset:51200
	ds_read_b128 v[214:217], v151 offset:52224
	ds_read_b128 v[218:221], v151 offset:53248
	ds_read_b128 v[236:239], v151 offset:54272
	ds_read_b128 v[240:243], v151 offset:55296
	ds_read_b128 v[244:247], v151 offset:56320
	s_add_u32 s100, s84, s60
	s_addc_u32 s101, s85, s61
	global_load_lds_dwordx4 v130, s[100:101]
	s_add_i32 m0, s9, 0x2000
	s_add_u32 s10, s84, 0x20080
	s_addc_u32 s11, s85, 0
	s_add_i32 s9, s12, s42
	global_load_lds_dwordx4 v134, s[100:101]
	s_mov_b32 m0, s9
	s_nop 0
	global_load_lds_dwordx4 v130, s[10:11]
	s_add_i32 m0, s9, 0x2000
	s_nop 0
	global_load_lds_dwordx4 v134, s[10:11]
	s_mov_b32 m0, s82
	s_add_u32 s100, s92, s60
	s_addc_u32 s101, s93, s61
	global_load_lds_dwordx4 v190, s[100:101]
	s_mov_b32 m0, s86
	s_nop 0
	global_load_lds_dwordx4 v132, s[100:101]
	s_waitcnt vmcnt(8)
	s_waitcnt lgkmcnt(0)
	s_barrier
	v_mfma_f32_16x16x32_bf16 v[62:65], v[152:155], v[194:197], v[62:65]
	v_mfma_f32_16x16x32_bf16 v[58:61], v[160:163], v[194:197], v[58:61]
	v_mfma_f32_16x16x32_bf16 v[54:57], v[152:155], v[210:213], v[54:57]
	v_mfma_f32_16x16x32_bf16 v[50:53], v[160:163], v[210:213], v[50:53]
	v_mfma_f32_16x16x32_bf16 v[46:49], v[152:155], v[218:221], v[46:49]
	v_mfma_f32_16x16x32_bf16 v[42:45], v[160:163], v[218:221], v[42:45]
	v_mfma_f32_16x16x32_bf16 v[38:41], v[152:155], v[240:243], v[38:41]
	v_mfma_f32_16x16x32_bf16 v[34:37], v[160:163], v[240:243], v[34:37]
	v_mfma_f32_16x16x32_bf16 v[62:65], v[156:159], v[206:209], v[62:65]
	v_mfma_f32_16x16x32_bf16 v[58:61], v[164:167], v[206:209], v[58:61]
	v_mfma_f32_16x16x32_bf16 v[54:57], v[156:159], v[214:217], v[54:57]
	v_mfma_f32_16x16x32_bf16 v[50:53], v[164:167], v[214:217], v[50:53]
	v_mfma_f32_16x16x32_bf16 v[46:49], v[156:159], v[236:239], v[46:49]
	v_mfma_f32_16x16x32_bf16 v[42:45], v[164:167], v[236:239], v[42:45]
	v_mfma_f32_16x16x32_bf16 v[38:41], v[156:159], v[244:247], v[38:41]
	v_mfma_f32_16x16x32_bf16 v[34:37], v[164:167], v[244:247], v[34:37]
	v_mfma_f32_16x16x32_bf16 v[30:33], v[168:171], v[194:197], v[30:33]
	v_mfma_f32_16x16x32_bf16 v[26:29], v[176:179], v[194:197], v[26:29]
	v_mfma_f32_16x16x32_bf16 v[22:25], v[168:171], v[210:213], v[22:25]
	v_mfma_f32_16x16x32_bf16 v[18:21], v[176:179], v[210:213], v[18:21]
	v_mfma_f32_16x16x32_bf16 v[14:17], v[168:171], v[218:221], v[14:17]
	v_mfma_f32_16x16x32_bf16 v[10:13], v[176:179], v[218:221], v[10:13]
	v_mfma_f32_16x16x32_bf16 v[6:9], v[168:171], v[240:243], v[6:9]
	v_mfma_f32_16x16x32_bf16 v[2:5], v[176:179], v[240:243], v[2:5]
	v_mfma_f32_16x16x32_bf16 v[30:33], v[172:175], v[206:209], v[30:33]
	v_mfma_f32_16x16x32_bf16 v[26:29], v[180:183], v[206:209], v[26:29]
	v_mfma_f32_16x16x32_bf16 v[22:25], v[172:175], v[214:217], v[22:25]
	v_mfma_f32_16x16x32_bf16 v[18:21], v[180:183], v[214:217], v[18:21]
	v_mfma_f32_16x16x32_bf16 v[14:17], v[172:175], v[236:239], v[14:17]
	v_mfma_f32_16x16x32_bf16 v[10:13], v[180:183], v[236:239], v[10:13]
	v_mfma_f32_16x16x32_bf16 v[6:9], v[172:175], v[244:247], v[6:9]
	v_mfma_f32_16x16x32_bf16 v[2:5], v[180:183], v[244:247], v[2:5]
	s_barrier
	s_add_i32 s8, s8, 2
	s_add_u32 s80, s80, 0x100
	s_addc_u32 s81, s81, 0
	s_cmp_gt_u32 s8, 29
	s_cbranch_scc0 .LBB0_1233
	s_and_b64 vcc, exec, s[62:63]
	s_cbranch_vccz .LBB0_1236
	s_barrier
